# also software-pipelined the three 256x128 GEMM k-loops (Y, resid1, resid2): A double-buffer, 4 B slots, ds_write/global_load interleaved, barrier before last 16 MFMAs
# speedup vs baseline: 1.0294x; 1.0294x over previous
; template <int BN, bool TRANS = false>
; DEV void gemm256_acc(f32x4 (&acc)[4][BN / 32], const bf16_t* __restrict__ A, int lda, int m_valid,
;                      const bf16_t* __restrict__ Bt, int ldb, int K, bf16_t* lds) {
;     ...
;   const bf16_t* ga0 = A + (size_t)min(crow, m_valid - 1) * lda + ckc;
;   const bf16_t* ga1 = A + (size_t)min(crow + 64, m_valid - 1) * lda + ckc;
;   const bf16_t* ga2 = A + (size_t)min(crow + 128, m_valid - 1) * lda + ckc;
;   const bf16_t* ga3 = A + (size_t)min(crow + 192, m_valid - 1) * lda + ckc;
;   const bf16_t* gb = Bt + (size_t)crow * ldb + ckc;
;   u32x4 ra0, ra1, ra2, ra3, rb0, rb1, rb2, rb3;
;     ...
;   const int nk = K / 64;
;   const int aoff = (wm * 64 + lr) * LS;
;   const int boff = (wn * (BN / 2) + lr) * LS;
;   GLOAD(0)
;   __syncthreads();
;   LSTORE(0)
;   GLOAD(64)
;   __syncthreads();
; DEV void phase_Y(const Params& p, unsigned char* ldsraw) {
;     ...
;     for (int br = 0; br < 3; br++) {
;       const bf16_t* Ab = (const bf16_t*)(ws + (br == 0 ? OFF_ORET : (br == 1 ? OFF_OHG : OFF_ODA))) + (size_t)row0 * 1024;
;       f32x4 acc[4][4];
; #pragma unroll
;       for (int i = 0; i < 4; i++)
; #pragma unroll
;         for (int j = 0; j < 4; j++) acc[i][j] = (f32x4){0.f, 0.f, 0.f, 0.f};
.LBB0_978:
	s_cmp_eq_u32 s11, 1
	v_mov_b32_e32 v30, v181
	s_cselect_b32 s12, s69, 0xc3bb700
	s_cmp_lg_u32 s11, 0
	s_cselect_b32 s12, s12, 0x114fb700
	v_ashrrev_i32_e32 v26, 3, v30
	v_min_i32_e32 v2, 0xff, v26
	s_add_u32 s14, s1, s12
	v_ashrrev_i32_e32 v3, 31, v2
	s_addc_u32 s15, s8, 0
	v_lshlrev_b64 v[2:3], 11, v[2:3]
	v_lshlrev_b32_e32 v0, 4, v30
	v_lshl_add_u64 v[2:3], s[14:15], 0, v[2:3]
	v_and_b32_e32 v0, 0x70, v0
	v_add_u32_e32 v31, 64, v26
	s_waitcnt vmcnt(1)
	v_lshl_add_u64 v[154:155], v[2:3], 0, v[0:1]
	v_min_i32_e32 v2, 0xff, v31
	v_ashrrev_i32_e32 v3, 31, v2
	v_lshlrev_b64 v[2:3], 11, v[2:3]
	v_lshl_add_u64 v[2:3], s[14:15], 0, v[2:3]
	v_add_u32_e32 v32, 0x80, v26
	v_lshl_add_u64 v[156:157], v[2:3], 0, v[0:1]
	v_min_i32_e32 v2, 0xff, v32
	v_ashrrev_i32_e32 v3, 31, v2
	v_lshlrev_b64 v[2:3], 11, v[2:3]
	s_lshl_b32 s12, s11, 10
	v_lshl_add_u64 v[2:3], s[14:15], 0, v[2:3]
	v_add_u32_e32 v33, 0xc0, v26
	s_add_u32 s16, s12, s6
	s_waitcnt vmcnt(0)
	v_lshl_add_u64 v[158:159], v[2:3], 0, v[0:1]
	v_min_i32_e32 v2, 0xff, v33
	s_addc_u32 s17, 0, s7
	v_ashrrev_i32_e32 v3, 31, v2
	s_lshl_b64 s[16:17], s[16:17], 11
	v_lshlrev_b64 v[2:3], 11, v[2:3]
	s_add_u32 s16, s80, s16
	v_lshl_add_u64 v[2:3], s[14:15], 0, v[2:3]
	v_ashrrev_i32_e32 v27, 31, v26
	s_addc_u32 s17, s81, s17
	v_lshl_add_u64 v[160:161], v[2:3], 0, v[0:1]
	v_lshlrev_b64 v[2:3], 11, v[26:27]
	v_lshl_add_u64 v[2:3], s[16:17], 0, v[2:3]
	v_lshl_add_u64 v[162:163], v[2:3], 0, v[0:1]
	v_add_co_u32_e32 v28, vcc, s63, v162
	global_load_dwordx4 v[2:5], v[154:155], off
	global_load_dwordx4 v[6:9], v[156:157], off
	global_load_dwordx4 v[10:13], v[158:159], off
	global_load_dwordx4 v[14:17], v[160:161], off
	v_addc_co_u32_e32 v29, vcc, 0, v163, vcc
	global_load_dwordx4 v[18:21], v[162:163], off
	global_load_dwordx4 v[22:25], v[28:29], off
	s_barrier
	global_load_dwordx4 v[42:45], v[154:155], off offset:128
	global_load_dwordx4 v[46:49], v[156:157], off offset:128
	global_load_dwordx4 v[50:53], v[158:159], off offset:128
	global_load_dwordx4 v[54:57], v[160:161], off offset:128
	global_load_dwordx4 v[58:61], v[162:163], off offset:128
	global_load_dwordx4 v[70:73], v[28:29], off offset:128
	v_lshrrev_b32_e32 v0, 4, v30
	v_xor_b32_e32 v35, v0, v30
	v_lshlrev_b32_e32 v35, 3, v35
	v_bfe_u32 v34, v30, 1, 3
	v_and_b32_e32 v35, 56, v35
	v_bitop3_b32 v0, v0, v34, 3 bitop3:0x6c
	v_lshlrev_b32_e32 v34, 6, v26
	v_lshlrev_b32_e32 v26, 7, v26
	v_lshlrev_b32_e32 v167, 1, v35
	v_lshlrev_b32_e32 v36, 6, v31
	v_lshlrev_b32_e32 v31, 7, v31
	v_lshlrev_b32_e32 v37, 6, v32
	v_lshlrev_b32_e32 v32, 7, v32
	v_lshlrev_b32_e32 v38, 6, v33
	v_lshlrev_b32_e32 v33, 7, v33
	v_add3_u32 v35, 0, v26, v167
	v_add3_u32 v40, 0, v31, v167
	v_add3_u32 v32, 0, v32, v167
	v_add3_u32 v33, 0, v33, v167
	v_add3_u32 v26, s66, v26, v167
	v_add3_u32 v31, s66, v31, v167
	v_lshrrev_b32_e32 v27, 1, v30
	v_lshlrev_b32_e32 v0, 3, v0
	v_xor_b32_e32 v39, 32, v0
	v_lshl_add_u64 v[164:165], v[162:163], 0, s[84:85]
	v_lshlrev_b32_e32 v170, 1, v34
	v_lshlrev_b32_e32 v171, 1, v36
	v_lshlrev_b32_e32 v172, 1, v37
	v_lshlrev_b32_e32 v173, 1, v38
	v_lshlrev_b32_e32 v174, 1, v39
	s_mov_b32 s13, 0
	v_mov_b32_e32 v28, v166
	v_mov_b32_e32 v29, v166
	v_mov_b32_e32 v34, 0
	v_mov_b32_e32 v36, v166
	v_mov_b32_e32 v37, v166
	v_mov_b32_e32 v38, 0
	v_mov_b32_e32 v39, v166
	v_mov_b32_e32 v41, v166
	v_mov_b32_e32 v62, 0
	v_mov_b32_e32 v63, v166
	v_mov_b32_e32 v64, v166
	v_mov_b32_e32 v65, v166
	v_mov_b32_e32 v66, 0
	v_mov_b32_e32 v67, v166
	v_mov_b32_e32 v68, v166
	v_mov_b32_e32 v69, v166
	v_mov_b32_e32 v74, 0
	s_waitcnt vmcnt(11)
	ds_write_b128 v35, v[2:5]
	s_waitcnt vmcnt(10)
	ds_write_b128 v40, v[6:9]
	s_waitcnt vmcnt(9)
	ds_write_b128 v32, v[10:13]
	s_waitcnt vmcnt(8)
	ds_write_b128 v33, v[14:17]
	s_waitcnt vmcnt(7)
	ds_write_b128 v26, v[18:21]
	s_waitcnt vmcnt(6)
	ds_write_b128 v31, v[22:25]
	v_lshlrev_b32_e32 v2, 7, v30
	v_and_b32_e32 v2, 0x2780, v2
	v_add_u32_e32 v168, s66, v2
	v_and_b32_e32 v2, 15, v30
	v_and_or_b32 v2, v27, s62, v2
	v_lshl_add_u32 v169, v2, 7, 0
	v_mov_b32_e32 v2, 0
	v_mov_b32_e32 v3, v166
	v_mov_b32_e32 v4, v166
	v_mov_b32_e32 v5, v166
	v_mov_b32_e32 v6, 0
	v_mov_b32_e32 v7, v166
	v_mov_b32_e32 v8, v166
	v_mov_b32_e32 v9, v166
	v_mov_b32_e32 v10, 0
	v_mov_b32_e32 v11, v166
	v_mov_b32_e32 v12, v166
	v_mov_b32_e32 v13, v166
	v_mov_b32_e32 v14, 0
	v_mov_b32_e32 v15, v166
	v_mov_b32_e32 v16, v166
	v_mov_b32_e32 v17, v166
	v_mov_b32_e32 v18, 0
	v_mov_b32_e32 v19, v166
	v_mov_b32_e32 v20, v166
	v_mov_b32_e32 v21, v166
	v_mov_b32_e32 v22, 0
	v_mov_b32_e32 v23, v166
	v_mov_b32_e32 v24, v166
	v_mov_b32_e32 v25, v166
	v_mov_b32_e32 v26, 0
	v_mov_b32_e32 v27, v166
	v_mov_b32_e32 v30, 0
	v_mov_b32_e32 v31, v166
	v_mov_b32_e32 v32, v166
	v_mov_b32_e32 v33, v166
	v_mov_b32_e32 v35, v166
	v_mov_b32_e32 v40, v166
	v_mov_b32_e32 v75, v166
	v_mov_b32_e32 v76, v166
	v_mov_b32_e32 v77, v166
	v_mov_b32_e32 v78, 0
	v_mov_b32_e32 v79, v166
	v_mov_b32_e32 v80, v166
	v_mov_b32_e32 v81, v166
	v_mov_b32_e32 v82, 0
	v_mov_b32_e32 v83, v166
	v_mov_b32_e32 v84, v166
	v_mov_b32_e32 v85, v166
	v_mov_b32_e32 v86, 0
	v_mov_b32_e32 v87, v166
	v_mov_b32_e32 v88, v166
	v_mov_b32_e32 v89, v166
	s_waitcnt lgkmcnt(0)
	s_barrier
	v_lshlrev_b32_e32 v203, 1, v0
	v_add_u32_e32 v216, v169, v203
	v_add_u32_e32 v206, v168, v203
	ds_read_b128 v[176:179], v216
	ds_read_b128 v[182:185], v216 offset:2048
	ds_read_b128 v[186:189], v216 offset:4096
	ds_read_b128 v[190:193], v216 offset:6144
	ds_read_b128 v[236:239], v206
	ds_read_b128 v[240:243], v206 offset:2048
	ds_read_b128 v[244:247], v206 offset:4096
	ds_read_b128 v[248:251], v206 offset:6144
; #define MFMA(a, b, c) __builtin_amdgcn_mfma_f32_16x16x32_bf16(a, b, c, 0, 0, 0)
; template <int BN, bool TRANS>
; DEV void gemm256_kstep(f32x4 (&acc)[4][BN / 32], const bf16_t* as, const bf16_t* bs, int sw) {
;   constexpr int LS = 64, NJ = BN / 32;
;   bf16x8 a[4];
; #pragma unroll
;   for (int i = 0; i < 4; i++) a[i] = *(const bf16x8*)(as + i * 16 * LS + sw);
; #pragma unroll
;   for (int j = 0; j < NJ; j++) {
;     bf16x8 bb = *(const bf16x8*)(bs + j * 16 * LS + sw);
; #pragma unroll
;     for (int i = 0; i < 4; i++) acc[i][j] = TRANS ? MFMA(a[i], bb, acc[i][j]) : MFMA(bb, a[i], acc[i][j]);
;   }
; }
; template <int BN, bool TRANS = false>
; DEV void gemm256_acc(f32x4 (&acc)[4][BN / 32], const bf16_t* __restrict__ A, int lda, int m_valid,
;                      const bf16_t* __restrict__ Bt, int ldb, int K, bf16_t* lds) {
;     ...
;   for (int kt = 0; kt < nk; kt++) {
;     const int cur = kt & 1;
;     gemm256_kstep<BN, TRANS>(acc, As + cur * A_SZ + aoff, Bs + cur * B_SZ + boff, sw0);
;     __builtin_amdgcn_sched_barrier(0);
;     LSTORE(cur ^ 1)
;     {
;       const int kn = (kt + 2 < nk) ? kt + 2 : nk - 1;
;       GLOAD(kn * 64)
;     }
;     __builtin_amdgcn_sched_barrier(0);
;     gemm256_kstep<BN, TRANS>(acc, As + cur * A_SZ + aoff, Bs + cur * B_SZ + boff, sw1);
;     __syncthreads();
;   }
.Lg128_979:
	s_min_u32 s14, s13, 13
	s_lshl_b32 s82, s14, 7
	s_and_b32 s14, s13, 1
	v_lshl_add_u32 v204, s14, 15, v169
	v_lshl_add_u32 v205, s14, 14, v168
	v_add_u32_e32 v204, v204, v174
	v_add_u32_e32 v205, v205, v174
	s_xor_b32 s14, s14, 1
	s_lshl_b32 s15, s14, 15
	v_lshl_add_u32 v206, s14, 14, v168
	s_lshl_b32 s14, s14, 14
	s_add_i32 s14, s14, 0x10000
	s_waitcnt lgkmcnt(3)
	v_mfma_f32_16x16x32_bf16 v[86:89], v[236:239], v[176:179], v[86:89]
	v_mfma_f32_16x16x32_bf16 v[66:69], v[236:239], v[182:185], v[66:69]
	v_mfma_f32_16x16x32_bf16 v[30:33], v[236:239], v[186:189], v[30:33]
	v_mfma_f32_16x16x32_bf16 v[14:17], v[236:239], v[190:193], v[14:17]
	ds_read_b128 v[236:239], v205
	ds_read_b128 v[220:223], v204
	v_add3_u32 v252, s15, v170, v167
	s_waitcnt vmcnt(5)
	ds_write_b128 v252, v[42:45]
	v_lshl_add_u64 v[42:43], v[154:155], 0, s[82:83]
	global_load_dwordx4 v[42:45], v[42:43], off offset:256
	s_waitcnt lgkmcnt(5)
	v_mfma_f32_16x16x32_bf16 v[82:85], v[240:243], v[176:179], v[82:85]
	v_mfma_f32_16x16x32_bf16 v[62:65], v[240:243], v[182:185], v[62:65]
	v_mfma_f32_16x16x32_bf16 v[26:29], v[240:243], v[186:189], v[26:29]
	v_mfma_f32_16x16x32_bf16 v[10:13], v[240:243], v[190:193], v[10:13]
	ds_read_b128 v[240:243], v205 offset:2048
	ds_read_b128 v[224:227], v204 offset:2048
	v_add3_u32 v252, s15, v171, v167
	s_waitcnt vmcnt(5)
	ds_write_b128 v252, v[46:49]
	v_lshl_add_u64 v[46:47], v[156:157], 0, s[82:83]
	global_load_dwordx4 v[46:49], v[46:47], off offset:256
	v_add3_u32 v252, s15, v172, v167
	s_waitcnt vmcnt(5)
	ds_write_b128 v252, v[50:53]
	v_lshl_add_u64 v[50:51], v[158:159], 0, s[82:83]
	global_load_dwordx4 v[50:53], v[50:51], off offset:256
	s_waitcnt lgkmcnt(8)
	v_mfma_f32_16x16x32_bf16 v[78:81], v[244:247], v[176:179], v[78:81]
	v_mfma_f32_16x16x32_bf16 v[38:41], v[244:247], v[182:185], v[38:41]
	v_mfma_f32_16x16x32_bf16 v[22:25], v[244:247], v[186:189], v[22:25]
	v_mfma_f32_16x16x32_bf16 v[6:9], v[244:247], v[190:193], v[6:9]
	ds_read_b128 v[244:247], v205 offset:4096
	ds_read_b128 v[228:231], v204 offset:4096
	v_add3_u32 v252, s15, v173, v167
	s_waitcnt vmcnt(5)
	ds_write_b128 v252, v[54:57]
	v_lshl_add_u64 v[54:55], v[160:161], 0, s[82:83]
	global_load_dwordx4 v[54:57], v[54:55], off offset:256
	v_add3_u32 v252, s14, v170, v167
	s_waitcnt vmcnt(5)
	ds_write_b128 v252, v[58:61]
	v_lshl_add_u64 v[58:59], v[162:163], 0, s[82:83]
	global_load_dwordx4 v[58:61], v[58:59], off offset:256
	s_waitcnt lgkmcnt(11)
	v_mfma_f32_16x16x32_bf16 v[74:77], v[248:251], v[176:179], v[74:77]
	v_mfma_f32_16x16x32_bf16 v[34:37], v[248:251], v[182:185], v[34:37]
	v_mfma_f32_16x16x32_bf16 v[18:21], v[248:251], v[186:189], v[18:21]
	v_mfma_f32_16x16x32_bf16 v[2:5], v[248:251], v[190:193], v[2:5]
	ds_read_b128 v[248:251], v205 offset:6144
	ds_read_b128 v[232:235], v204 offset:6144
	v_add3_u32 v252, s14, v171, v167
	s_waitcnt vmcnt(5)
	ds_write_b128 v252, v[70:73]
	v_lshl_add_u64 v[70:71], v[164:165], 0, s[82:83]
	global_load_dwordx4 v[70:73], v[70:71], off offset:256
	v_lshlrev_b32_e32 v203, 1, v0
	v_add3_u32 v216, v169, s15, v203
	v_add_u32_e32 v206, v206, v203
	s_waitcnt lgkmcnt(0)
	s_barrier
	ds_read_b128 v[176:179], v216
	ds_read_b128 v[182:185], v216 offset:2048
	ds_read_b128 v[186:189], v216 offset:4096
	ds_read_b128 v[190:193], v216 offset:6144
	v_mfma_f32_16x16x32_bf16 v[86:89], v[236:239], v[220:223], v[86:89]
	v_mfma_f32_16x16x32_bf16 v[66:69], v[236:239], v[224:227], v[66:69]
	v_mfma_f32_16x16x32_bf16 v[30:33], v[236:239], v[228:231], v[30:33]
	v_mfma_f32_16x16x32_bf16 v[14:17], v[236:239], v[232:235], v[14:17]
	ds_read_b128 v[236:239], v206
	v_mfma_f32_16x16x32_bf16 v[82:85], v[240:243], v[220:223], v[82:85]
	v_mfma_f32_16x16x32_bf16 v[62:65], v[240:243], v[224:227], v[62:65]
	v_mfma_f32_16x16x32_bf16 v[26:29], v[240:243], v[228:231], v[26:29]
	v_mfma_f32_16x16x32_bf16 v[10:13], v[240:243], v[232:235], v[10:13]
	ds_read_b128 v[240:243], v206 offset:2048
	v_mfma_f32_16x16x32_bf16 v[78:81], v[244:247], v[220:223], v[78:81]
	v_mfma_f32_16x16x32_bf16 v[38:41], v[244:247], v[224:227], v[38:41]
	v_mfma_f32_16x16x32_bf16 v[22:25], v[244:247], v[228:231], v[22:25]
	v_mfma_f32_16x16x32_bf16 v[6:9], v[244:247], v[232:235], v[6:9]
	ds_read_b128 v[244:247], v206 offset:4096
	v_mfma_f32_16x16x32_bf16 v[74:77], v[248:251], v[220:223], v[74:77]
	v_mfma_f32_16x16x32_bf16 v[34:37], v[248:251], v[224:227], v[34:37]
	v_mfma_f32_16x16x32_bf16 v[18:21], v[248:251], v[228:231], v[18:21]
	v_mfma_f32_16x16x32_bf16 v[2:5], v[248:251], v[232:235], v[2:5]
	ds_read_b128 v[248:251], v206 offset:6144
	s_add_i32 s13, s13, 1
	s_cmp_lg_u32 s13, 16
	s_cbranch_scc1 .Lg128_979
; DEV int get_tid() { int t = threadIdx.x; asm volatile("" : "+v"(t)); return t; }
; DEV float bf2f(bf16_t h) { return __uint_as_float(((unsigned)h) << 16); }
; DEV void phase_Y(const Params& p, unsigned char* ldsraw) {
;     ...
;       const int tid = get_tid(), lane = tid & 63, wave = tid >> 6, wm = wave >> 1, wn = wave & 1; const int lr = lane & 15, lg = lane >> 4;
; #pragma unroll
;       for (int i = 0; i < 4; i++) {
;         const int t = row0 + wm * 64 + i * 16 + lr;
; #pragma unroll
;         for (int j = 0; j < 4; j++) {
;           uint2 gv = *(const uint2*)(G + (size_t)t * 3072 + br * 1024 + nt * 128 + wn * 64 + j * 16 + lg * 4);
;           y[i][j][0] += bf2f((bf16_t)(gv.x & 0xffff)) * acc[i][j][0];
;           y[i][j][1] += bf2f((bf16_t)(gv.x >> 16)) * acc[i][j][1];
;           y[i][j][2] += bf2f((bf16_t)(gv.y & 0xffff)) * acc[i][j][2];
;           y[i][j][3] += bf2f((bf16_t)(gv.y >> 16)) * acc[i][j][3];
;         }
;       }
	s_waitcnt lgkmcnt(0)
	s_waitcnt vmcnt(5)
	v_mov_b32_e32 v44, v181
	s_lshl_b32 s12, s12, 1
	v_ashrrev_i32_e32 v42, 1, v44
	v_and_b32_e32 v0, 64, v44
	v_and_b32_e32 v42, 0xffffffc0, v42
	s_add_u32 s12, s9, s12
	v_add_u32_e32 v42, s0, v42
	s_addc_u32 s13, s10, 0
	v_lshlrev_b32_e32 v0, 1, v0
	s_waitcnt vmcnt(3)
	v_and_or_b32 v50, v44, 15, v42
	v_lshl_add_u64 v[42:43], s[12:13], 0, v[0:1]
	v_lshrrev_b32_e32 v0, 1, v44
	v_and_b32_e32 v0, 24, v0
	v_lshl_add_u64 v[42:43], v[42:43], 0, v[0:1]
	v_mad_i64_i32 v[44:45], s[12:13], v50, s72, v[42:43]
	global_load_dwordx2 v[46:47], v[44:45], off
	v_or_b32_e32 v0, 16, v50
	s_add_i32 s11, s11, 1
	s_cmp_eq_u32 s11, 3
	s_waitcnt vmcnt(0)
	v_lshlrev_b32_e32 v48, 16, v46
	v_and_b32_e32 v49, 0xffff0000, v46
	v_lshlrev_b32_e32 v46, 16, v47
	v_and_b32_e32 v47, 0xffff0000, v47
	v_pk_fma_f32 v[152:153], v[88:89], v[46:47], v[152:153]
	global_load_dwordx2 v[46:47], v[44:45], off offset:32
	v_pk_fma_f32 v[150:151], v[86:87], v[48:49], v[150:151]
	s_waitcnt vmcnt(0)
	v_lshlrev_b32_e32 v48, 16, v46
	v_and_b32_e32 v49, 0xffff0000, v46
	v_lshlrev_b32_e32 v46, 16, v47
	v_and_b32_e32 v47, 0xffff0000, v47
	v_pk_fma_f32 v[148:149], v[84:85], v[46:47], v[148:149]
	global_load_dwordx2 v[46:47], v[44:45], off offset:64
	v_pk_fma_f32 v[146:147], v[82:83], v[48:49], v[146:147]
	global_load_dwordx2 v[44:45], v[44:45], off offset:96
	s_waitcnt vmcnt(1)
	v_lshlrev_b32_e32 v48, 16, v46
	v_and_b32_e32 v49, 0xffff0000, v46
	v_lshlrev_b32_e32 v46, 16, v47
	v_and_b32_e32 v47, 0xffff0000, v47
	v_pk_fma_f32 v[144:145], v[80:81], v[46:47], v[144:145]
	s_waitcnt vmcnt(0)
	v_lshlrev_b32_e32 v46, 16, v44
	v_and_b32_e32 v47, 0xffff0000, v44
	v_lshlrev_b32_e32 v44, 16, v45
	v_and_b32_e32 v45, 0xffff0000, v45
	v_pk_fma_f32 v[140:141], v[76:77], v[44:45], v[140:141]
	v_mad_i64_i32 v[44:45], s[12:13], v0, s72, v[42:43]
	v_pk_fma_f32 v[138:139], v[74:75], v[46:47], v[138:139]
	global_load_dwordx2 v[46:47], v[44:45], off
	v_pk_fma_f32 v[142:143], v[78:79], v[48:49], v[142:143]
	v_or_b32_e32 v0, 32, v50
	s_waitcnt vmcnt(0)
	v_lshlrev_b32_e32 v48, 16, v46
	v_and_b32_e32 v49, 0xffff0000, v46
	v_lshlrev_b32_e32 v46, 16, v47
	v_and_b32_e32 v47, 0xffff0000, v47
	v_pk_fma_f32 v[136:137], v[68:69], v[46:47], v[136:137]
	global_load_dwordx2 v[46:47], v[44:45], off offset:32
	v_pk_fma_f32 v[134:135], v[66:67], v[48:49], v[134:135]
	s_waitcnt vmcnt(0)
	v_lshlrev_b32_e32 v48, 16, v46
	v_and_b32_e32 v49, 0xffff0000, v46
	v_lshlrev_b32_e32 v46, 16, v47
	v_and_b32_e32 v47, 0xffff0000, v47
	v_pk_fma_f32 v[132:133], v[64:65], v[46:47], v[132:133]
	global_load_dwordx2 v[46:47], v[44:45], off offset:64
	v_pk_fma_f32 v[130:131], v[62:63], v[48:49], v[130:131]
	s_waitcnt vmcnt(0)
	v_lshlrev_b32_e32 v48, 16, v46
	v_and_b32_e32 v49, 0xffff0000, v46
	v_pk_fma_f32 v[126:127], v[38:39], v[48:49], v[126:127]
	v_lshlrev_b32_e32 v38, 16, v47
	v_and_b32_e32 v39, 0xffff0000, v47
	v_pk_fma_f32 v[128:129], v[40:41], v[38:39], v[128:129]
	global_load_dwordx2 v[38:39], v[44:45], off offset:96
	s_waitcnt vmcnt(0)
	v_lshlrev_b32_e32 v40, 16, v38
	v_and_b32_e32 v41, 0xffff0000, v38
	v_pk_fma_f32 v[122:123], v[34:35], v[40:41], v[122:123]
	v_lshlrev_b32_e32 v34, 16, v39
	v_and_b32_e32 v35, 0xffff0000, v39
	v_pk_fma_f32 v[124:125], v[36:37], v[34:35], v[124:125]
	v_mad_i64_i32 v[34:35], s[12:13], v0, s72, v[42:43]
	global_load_dwordx2 v[36:37], v[34:35], off
	v_or_b32_e32 v0, 48, v50
	s_waitcnt vmcnt(0)
	v_lshlrev_b32_e32 v38, 16, v36
	v_and_b32_e32 v39, 0xffff0000, v36
	v_pk_fma_f32 v[118:119], v[30:31], v[38:39], v[118:119]
	v_lshlrev_b32_e32 v30, 16, v37
	v_and_b32_e32 v31, 0xffff0000, v37
	v_pk_fma_f32 v[120:121], v[32:33], v[30:31], v[120:121]
	global_load_dwordx2 v[30:31], v[34:35], off offset:32
	s_waitcnt vmcnt(0)
	v_lshlrev_b32_e32 v32, 16, v30
	v_and_b32_e32 v33, 0xffff0000, v30
	v_pk_fma_f32 v[114:115], v[26:27], v[32:33], v[114:115]
	v_lshlrev_b32_e32 v26, 16, v31
	v_and_b32_e32 v27, 0xffff0000, v31
	v_pk_fma_f32 v[116:117], v[28:29], v[26:27], v[116:117]
	global_load_dwordx2 v[26:27], v[34:35], off offset:64
	s_waitcnt vmcnt(0)
	v_lshlrev_b32_e32 v28, 16, v26
	v_and_b32_e32 v29, 0xffff0000, v26
	v_pk_fma_f32 v[110:111], v[22:23], v[28:29], v[110:111]
	v_lshlrev_b32_e32 v22, 16, v27
	v_and_b32_e32 v23, 0xffff0000, v27
	v_pk_fma_f32 v[112:113], v[24:25], v[22:23], v[112:113]
	global_load_dwordx2 v[22:23], v[34:35], off offset:96
	s_waitcnt vmcnt(0)
	v_lshlrev_b32_e32 v24, 16, v22
	v_and_b32_e32 v25, 0xffff0000, v22
	v_pk_fma_f32 v[106:107], v[18:19], v[24:25], v[106:107]
	v_lshlrev_b32_e32 v18, 16, v23
	v_and_b32_e32 v19, 0xffff0000, v23
	v_pk_fma_f32 v[108:109], v[20:21], v[18:19], v[108:109]
	v_mad_i64_i32 v[18:19], s[12:13], v0, s72, v[42:43]
	global_load_dwordx2 v[20:21], v[18:19], off
	s_waitcnt vmcnt(0)
	v_lshlrev_b32_e32 v22, 16, v20
	v_and_b32_e32 v23, 0xffff0000, v20
	v_pk_fma_f32 v[102:103], v[14:15], v[22:23], v[102:103]
	v_lshlrev_b32_e32 v14, 16, v21
	v_and_b32_e32 v15, 0xffff0000, v21
	v_pk_fma_f32 v[104:105], v[16:17], v[14:15], v[104:105]
	global_load_dwordx2 v[14:15], v[18:19], off offset:32
	s_waitcnt vmcnt(0)
	v_lshlrev_b32_e32 v16, 16, v14
	v_and_b32_e32 v17, 0xffff0000, v14
	v_pk_fma_f32 v[98:99], v[10:11], v[16:17], v[98:99]
	v_lshlrev_b32_e32 v10, 16, v15
	v_and_b32_e32 v11, 0xffff0000, v15
	v_pk_fma_f32 v[100:101], v[12:13], v[10:11], v[100:101]
	global_load_dwordx2 v[10:11], v[18:19], off offset:64
	s_waitcnt vmcnt(0)
	v_lshlrev_b32_e32 v12, 16, v10
	v_and_b32_e32 v13, 0xffff0000, v10
	v_pk_fma_f32 v[94:95], v[6:7], v[12:13], v[94:95]
	v_lshlrev_b32_e32 v6, 16, v11
	v_and_b32_e32 v7, 0xffff0000, v11
	v_pk_fma_f32 v[96:97], v[8:9], v[6:7], v[96:97]
	global_load_dwordx2 v[6:7], v[18:19], off offset:96
	s_waitcnt vmcnt(0)
	v_lshlrev_b32_e32 v8, 16, v6
	v_and_b32_e32 v9, 0xffff0000, v6
	v_pk_fma_f32 v[90:91], v[2:3], v[8:9], v[90:91]
	v_lshlrev_b32_e32 v2, 16, v7
	v_and_b32_e32 v3, 0xffff0000, v7
	v_pk_fma_f32 v[92:93], v[4:5], v[2:3], v[92:93]
	s_cbranch_scc0 .LBB0_978
; DEV int get_tid() { int t = threadIdx.x; asm volatile("" : "+v"(t)); return t; }
; DEV uint2 pack4(f32x4 v) { uint2 r; r.x = pack2(v[0], v[1]); r.y = pack2(v[2], v[3]); return r; }
; DEV void phase_Y(const Params& p, unsigned char* ldsraw) {
;     ...
;     const int tid = get_tid(), lane = tid & 63, wave = tid >> 6, wm = wave >> 1, wn = wave & 1; const int lr = lane & 15, lg = lane >> 4;
; #pragma unroll
;     for (int i = 0; i < 4; i++) {
;       const int t = row0 + wm * 64 + i * 16 + lr;
; #pragma unroll
;       for (int j = 0; j < 4; j++)
;         *(uint2*)(Y + (size_t)t * 1024 + nt * 128 + wn * 64 + j * 16 + lg * 4) = pack4(y[i][j]);
;     }
	v_mov_b32_e32 v3, v181
	v_cvt_pk_bf16_f32 v8, v150, v151
	v_ashrrev_i32_e32 v2, 1, v3
	v_and_b32_e32 v2, 0xffffffc0, v2
	v_and_b32_e32 v0, 64, v3
	v_add_u32_e32 v2, s0, v2
	s_add_u32 s0, s90, s4
	s_addc_u32 s1, s91, s5
	v_lshlrev_b32_e32 v0, 1, v0
	v_and_or_b32 v2, v3, 15, v2
	v_lshl_add_u64 v[4:5], s[0:1], 0, v[0:1]
	v_lshrrev_b32_e32 v0, 1, v3
	v_and_b32_e32 v0, 24, v0
	v_ashrrev_i32_e32 v3, 31, v2
	v_lshl_add_u64 v[4:5], v[4:5], 0, v[0:1]
	v_lshlrev_b64 v[6:7], 11, v[2:3]
	v_lshl_add_u64 v[6:7], v[4:5], 0, v[6:7]
	v_cvt_pk_bf16_f32 v9, v152, v153
	global_store_dwordx2 v[6:7], v[8:9], off
	v_cvt_pk_bf16_f32 v8, v146, v147
	v_cvt_pk_bf16_f32 v9, v148, v149
	global_store_dwordx2 v[6:7], v[8:9], off offset:32
	v_cvt_pk_bf16_f32 v8, v142, v143
	v_cvt_pk_bf16_f32 v9, v144, v145
	global_store_dwordx2 v[6:7], v[8:9], off offset:64
	v_cvt_pk_bf16_f32 v8, v138, v139
	v_cvt_pk_bf16_f32 v9, v140, v141
	global_store_dwordx2 v[6:7], v[8:9], off offset:96
	v_or_b32_e32 v6, 16, v2
	v_ashrrev_i32_e32 v7, 31, v6
	v_lshlrev_b64 v[6:7], 11, v[6:7]
	v_lshl_add_u64 v[6:7], v[4:5], 0, v[6:7]
	v_cvt_pk_bf16_f32 v8, v134, v135
	v_cvt_pk_bf16_f32 v9, v136, v137
	global_store_dwordx2 v[6:7], v[8:9], off
	v_cvt_pk_bf16_f32 v8, v130, v131
	v_cvt_pk_bf16_f32 v9, v132, v133
	global_store_dwordx2 v[6:7], v[8:9], off offset:32
	v_cvt_pk_bf16_f32 v8, v126, v127
	v_cvt_pk_bf16_f32 v9, v128, v129
	global_store_dwordx2 v[6:7], v[8:9], off offset:64
	v_cvt_pk_bf16_f32 v8, v122, v123
	v_cvt_pk_bf16_f32 v9, v124, v125
	global_store_dwordx2 v[6:7], v[8:9], off offset:96
	v_or_b32_e32 v6, 32, v2
	v_or_b32_e32 v2, 48, v2
	v_ashrrev_i32_e32 v7, 31, v6
	v_ashrrev_i32_e32 v3, 31, v2
	v_lshlrev_b64 v[6:7], 11, v[6:7]
	v_lshlrev_b64 v[2:3], 11, v[2:3]
	v_lshl_add_u64 v[6:7], v[4:5], 0, v[6:7]
	v_cvt_pk_bf16_f32 v8, v118, v119
	v_cvt_pk_bf16_f32 v9, v120, v121
	v_lshl_add_u64 v[2:3], v[4:5], 0, v[2:3]
	v_cvt_pk_bf16_f32 v4, v102, v103
	v_cvt_pk_bf16_f32 v5, v104, v105
	global_store_dwordx2 v[6:7], v[8:9], off
	v_cvt_pk_bf16_f32 v8, v114, v115
	v_cvt_pk_bf16_f32 v9, v116, v117
	global_store_dwordx2 v[2:3], v[4:5], off
	v_cvt_pk_bf16_f32 v4, v98, v99
	v_cvt_pk_bf16_f32 v5, v100, v101
	global_store_dwordx2 v[6:7], v[8:9], off offset:32
	v_cvt_pk_bf16_f32 v8, v110, v111
	v_cvt_pk_bf16_f32 v9, v112, v113
	global_store_dwordx2 v[2:3], v[4:5], off offset:32
	v_cvt_pk_bf16_f32 v4, v94, v95
	v_cvt_pk_bf16_f32 v5, v96, v97
	global_store_dwordx2 v[6:7], v[8:9], off offset:64
	v_cvt_pk_bf16_f32 v8, v106, v107
	v_cvt_pk_bf16_f32 v9, v108, v109
	global_store_dwordx2 v[2:3], v[4:5], off offset:64
	v_cvt_pk_bf16_f32 v4, v90, v91
	v_cvt_pk_bf16_f32 v5, v92, v93
	s_mov_b64 s[0:1], 0
	global_store_dwordx2 v[6:7], v[8:9], off offset:96
	global_store_dwordx2 v[2:3], v[4:5], off offset:96

; template <int BN, bool TRANS = false>
; DEV void gemm256_acc(f32x4 (&acc)[4][BN / 32], const bf16_t* __restrict__ A, int lda, int m_valid,
;                      const bf16_t* __restrict__ Bt, int ldb, int K, bf16_t* lds) {
;     ...
;   const bf16_t* ga0 = A + (size_t)min(crow, m_valid - 1) * lda + ckc;
;   const bf16_t* ga1 = A + (size_t)min(crow + 64, m_valid - 1) * lda + ckc;
;   const bf16_t* ga2 = A + (size_t)min(crow + 128, m_valid - 1) * lda + ckc;
;   const bf16_t* ga3 = A + (size_t)min(crow + 192, m_valid - 1) * lda + ckc;
;   const bf16_t* gb = Bt + (size_t)crow * ldb + ckc;
;   u32x4 ra0, ra1, ra2, ra3, rb0, rb1, rb2, rb3;
;     ...
;   const int nk = K / 64;
;   const int aoff = (wm * 64 + lr) * LS;
;   const int boff = (wn * (BN / 2) + lr) * LS;
;   GLOAD(0)
;   __syncthreads();
;   LSTORE(0)
;   GLOAD(64)
;   __syncthreads();
; DEV void phase_resid(const Params& p, int b, const bf16_t* A, int K, const bf16_t* Wt, unsigned char* ldsraw) {
;     ...
;     int nt, mt; tile_map(item, 32, 4, mt, nt);
;     const int row0 = 128 + mt * 256;
;     f32x4 acc[4][4];
; #pragma unroll
;     for (int i = 0; i < 4; i++)
; #pragma unroll
;       for (int j = 0; j < 4; j++) acc[i][j] = (f32x4){0.f, 0.f, 0.f, 0.f};
;     gemm256_acc<128>(acc, A + (size_t)row0 * K, K, 256, Wt + (size_t)nt * 128 * K, K, K, lds);
.LBB0_1045:
	s_cmpk_lt_i32 s2, 0x100
	s_mov_b64 s[0:1], -1
	s_cbranch_scc0 .LBB0_1049
	s_ashr_i32 s0, s2, 31
	s_lshr_b32 s0, s0, 25
	s_add_i32 s0, s2, s0
	s_ashr_i32 s1, s0, 7
	s_and_b32 s0, s0, 0xffffff80
	s_sub_i32 s0, s2, s0
	s_ashr_i32 s4, s0, 31
	s_lshr_b32 s4, s4, 30
	s_add_i32 s4, s0, s4
	s_ashr_i32 s4, s4, 2
	s_sub_i32 s1, s1, s4
	s_lshl_b32 s4, s4, 8
	s_bitset1_b32 s4, 7
	v_mov_b32_e32 v30, v181
	s_lshl_b32 s1, s1, 2
	s_ashr_i32 s5, s4, 31
	s_add_i32 s0, s1, s0
	v_ashrrev_i32_e32 v26, 3, v30
	s_lshl_b64 s[10:11], s[4:5], 11
	v_min_i32_e32 v2, 0xff, v26
	s_add_u32 s10, s90, s10
	v_ashrrev_i32_e32 v3, 31, v2
	s_addc_u32 s11, s91, s11
	v_lshlrev_b64 v[2:3], 11, v[2:3]
	v_lshlrev_b32_e32 v0, 4, v30
	v_lshl_add_u64 v[2:3], s[10:11], 0, v[2:3]
	v_and_b32_e32 v0, 0x70, v0
	v_add_u32_e32 v31, 64, v26
	v_lshl_add_u64 v[90:91], v[2:3], 0, v[0:1]
	v_min_i32_e32 v2, 0xff, v31
	v_ashrrev_i32_e32 v3, 31, v2
	v_lshlrev_b64 v[2:3], 11, v[2:3]
	v_lshl_add_u64 v[2:3], s[10:11], 0, v[2:3]
	v_add_u32_e32 v32, 0x80, v26
	v_lshl_add_u64 v[92:93], v[2:3], 0, v[0:1]
	v_min_i32_e32 v2, 0xff, v32
	v_ashrrev_i32_e32 v3, 31, v2
	v_lshlrev_b64 v[2:3], 11, v[2:3]
	v_lshl_add_u64 v[2:3], s[10:11], 0, v[2:3]
	v_add_u32_e32 v33, 0xc0, v26
	v_lshl_add_u64 v[94:95], v[2:3], 0, v[0:1]
	v_min_i32_e32 v2, 0xff, v33
	s_ashr_i32 s1, s0, 31
	v_ashrrev_i32_e32 v3, 31, v2
	s_lshl_b64 s[12:13], s[0:1], 18
	v_lshlrev_b64 v[2:3], 11, v[2:3]
	s_add_u32 s12, s14, s12
	v_lshl_add_u64 v[2:3], s[10:11], 0, v[2:3]
	v_ashrrev_i32_e32 v27, 31, v26
	s_addc_u32 s13, s15, s13
	v_lshl_add_u64 v[96:97], v[2:3], 0, v[0:1]
	v_lshlrev_b64 v[2:3], 11, v[26:27]
	v_lshl_add_u64 v[2:3], s[12:13], 0, v[2:3]
	v_lshl_add_u64 v[98:99], v[2:3], 0, v[0:1]
	global_load_dwordx4 v[2:5], v[90:91], off
	global_load_dwordx4 v[6:9], v[92:93], off
	global_load_dwordx4 v[10:13], v[94:95], off
	global_load_dwordx4 v[14:17], v[96:97], off
	global_load_dwordx4 v[18:21], v[98:99], off
	v_lshrrev_b32_e32 v0, 4, v30
	v_xor_b32_e32 v35, v0, v30
	v_lshlrev_b32_e32 v35, 3, v35
	v_bfe_u32 v34, v30, 1, 3
	v_and_b32_e32 v35, 56, v35
	v_add_co_u32_e32 v28, vcc, s63, v98
	v_bitop3_b32 v0, v0, v34, 3 bitop3:0x6c
	v_lshlrev_b32_e32 v34, 6, v26
	v_lshlrev_b32_e32 v26, 7, v26
	v_lshlrev_b32_e32 v102, 1, v35
	v_addc_co_u32_e32 v29, vcc, 0, v99, vcc
	v_lshlrev_b32_e32 v36, 6, v31
	v_lshlrev_b32_e32 v31, 7, v31
	v_lshlrev_b32_e32 v37, 6, v32
	v_lshlrev_b32_e32 v32, 7, v32
	v_lshlrev_b32_e32 v58, 6, v33
	v_lshlrev_b32_e32 v33, 7, v33
	v_add3_u32 v35, 0, v26, v102
	global_load_dwordx4 v[22:25], v[28:29], off
	v_add3_u32 v46, 0, v31, v102
	v_add3_u32 v32, 0, v32, v102
	v_add3_u32 v33, 0, v33, v102
	v_add3_u32 v26, s66, v26, v102
	s_waitcnt vmcnt(63) expcnt(7) lgkmcnt(15)
	s_barrier
	global_load_dwordx4 v[38:41], v[90:91], off offset:128
	global_load_dwordx4 v[42:45], v[92:93], off offset:128
	v_lshrrev_b32_e32 v27, 1, v30
	v_lshlrev_b32_e32 v0, 3, v0
	v_xor_b32_e32 v59, 32, v0
	v_add3_u32 v31, s66, v31, v102
	s_mov_b32 s1, 0
	v_lshl_add_u64 v[100:101], v[98:99], 0, s[84:85]
	v_lshlrev_b32_e32 v105, 1, v34
	v_lshlrev_b32_e32 v106, 1, v36
	v_lshlrev_b32_e32 v107, 1, v37
	v_lshlrev_b32_e32 v108, 1, v58
	v_lshlrev_b32_e32 v109, 1, v59
	s_waitcnt vmcnt(7)
	ds_write_b128 v35, v[2:5]
	s_waitcnt vmcnt(6)
	ds_write_b128 v46, v[6:9]
	s_waitcnt vmcnt(5)
	ds_write_b128 v32, v[10:13]
	s_waitcnt vmcnt(4)
	ds_write_b128 v33, v[14:17]
	s_waitcnt vmcnt(3)
	ds_write_b128 v26, v[18:21]
	global_load_dwordx4 v[46:49], v[94:95], off offset:128
	global_load_dwordx4 v[50:53], v[96:97], off offset:128
	global_load_dwordx4 v[54:57], v[98:99], off offset:128
	global_load_dwordx4 v[70:73], v[28:29], off offset:128
	v_lshlrev_b32_e32 v2, 7, v30
	v_and_b32_e32 v2, 0x2780, v2
	v_add_u32_e32 v103, s66, v2
	v_and_b32_e32 v2, 15, v30
	v_and_or_b32 v2, v27, s62, v2
	v_lshl_add_u32 v104, v2, 7, 0
	v_mov_b32_e32 v2, 0
	v_mov_b32_e32 v3, v2
	v_mov_b32_e32 v4, v2
	v_mov_b32_e32 v5, v2
	v_mov_b32_e32 v6, v2
	v_mov_b32_e32 v7, v2
	v_mov_b32_e32 v8, v2
	v_mov_b32_e32 v9, v2
	v_mov_b32_e32 v10, v2
	v_mov_b32_e32 v11, v2
	v_mov_b32_e32 v12, v2
	v_mov_b32_e32 v13, v2
	v_mov_b32_e32 v14, v2
	s_waitcnt vmcnt(6)
	ds_write_b128 v31, v[22:25]
	v_mov_b32_e32 v15, v2
	v_mov_b32_e32 v16, v2
	v_mov_b32_e32 v17, v2
	v_mov_b32_e32 v18, v2
	v_mov_b32_e32 v19, v2
	v_mov_b32_e32 v20, v2
	v_mov_b32_e32 v21, v2
	v_mov_b32_e32 v22, v2
	v_mov_b32_e32 v23, v2
	v_mov_b32_e32 v24, v2
	v_mov_b32_e32 v25, v2
	v_mov_b32_e32 v26, v2
	v_mov_b32_e32 v27, v2
	v_mov_b32_e32 v28, v2
	v_mov_b32_e32 v29, v2
	v_mov_b32_e32 v30, v2
	v_mov_b32_e32 v31, v2
	v_mov_b32_e32 v32, v2
	v_mov_b32_e32 v33, v2
	v_mov_b32_e32 v34, v2
	v_mov_b32_e32 v35, v2
	v_mov_b32_e32 v36, v2
	v_mov_b32_e32 v37, v2
	v_mov_b32_e32 v58, v2
	v_mov_b32_e32 v59, v2
	v_mov_b32_e32 v60, v2
	v_mov_b32_e32 v61, v2
	v_mov_b32_e32 v62, v2
	v_mov_b32_e32 v63, v2
	v_mov_b32_e32 v64, v2
	v_mov_b32_e32 v65, v2
	v_mov_b32_e32 v66, v2
	v_mov_b32_e32 v67, v2
	v_mov_b32_e32 v68, v2
	v_mov_b32_e32 v69, v2
	v_mov_b32_e32 v74, v2
	v_mov_b32_e32 v75, v2
	v_mov_b32_e32 v76, v2
	v_mov_b32_e32 v77, v2
	v_mov_b32_e32 v78, v2
	v_mov_b32_e32 v79, v2
	v_mov_b32_e32 v80, v2
	v_mov_b32_e32 v81, v2
	v_mov_b32_e32 v82, v2
	v_mov_b32_e32 v83, v2
	v_mov_b32_e32 v84, v2
	v_mov_b32_e32 v85, v2
	v_mov_b32_e32 v86, v2
	v_mov_b32_e32 v87, v2
	v_mov_b32_e32 v88, v2
	v_mov_b32_e32 v89, v2
	s_waitcnt lgkmcnt(0)
	s_barrier
	v_lshlrev_b32_e32 v203, 1, v0
	v_add_u32_e32 v216, v104, v203
	v_add_u32_e32 v206, v103, v203
	ds_read_b128 v[110:113], v216
	ds_read_b128 v[114:117], v216 offset:2048
	ds_read_b128 v[118:121], v216 offset:4096
	ds_read_b128 v[122:125], v216 offset:6144
	ds_read_b128 v[236:239], v206
	ds_read_b128 v[240:243], v206 offset:2048
	ds_read_b128 v[244:247], v206 offset:4096
	ds_read_b128 v[248:251], v206 offset:6144
; #define MFMA(a, b, c) __builtin_amdgcn_mfma_f32_16x16x32_bf16(a, b, c, 0, 0, 0)
; template <int BN, bool TRANS>
; DEV void gemm256_kstep(f32x4 (&acc)[4][BN / 32], const bf16_t* as, const bf16_t* bs, int sw) {
;   constexpr int LS = 64, NJ = BN / 32;
;   bf16x8 a[4];
; #pragma unroll
;   for (int i = 0; i < 4; i++) a[i] = *(const bf16x8*)(as + i * 16 * LS + sw);
; #pragma unroll
;   for (int j = 0; j < NJ; j++) {
;     bf16x8 bb = *(const bf16x8*)(bs + j * 16 * LS + sw);
; #pragma unroll
;     for (int i = 0; i < 4; i++) acc[i][j] = TRANS ? MFMA(a[i], bb, acc[i][j]) : MFMA(bb, a[i], acc[i][j]);
;   }
; }
; template <int BN, bool TRANS = false>
; DEV void gemm256_acc(f32x4 (&acc)[4][BN / 32], const bf16_t* __restrict__ A, int lda, int m_valid,
;                      const bf16_t* __restrict__ Bt, int ldb, int K, bf16_t* lds) {
;     ...
;   for (int kt = 0; kt < nk; kt++) {
;     const int cur = kt & 1;
;     gemm256_kstep<BN, TRANS>(acc, As + cur * A_SZ + aoff, Bs + cur * B_SZ + boff, sw0);
;     __builtin_amdgcn_sched_barrier(0);
;     LSTORE(cur ^ 1)
;     {
;       const int kn = (kt + 2 < nk) ? kt + 2 : nk - 1;
;       GLOAD(kn * 64)
;     }
;     __builtin_amdgcn_sched_barrier(0);
;     gemm256_kstep<BN, TRANS>(acc, As + cur * A_SZ + aoff, Bs + cur * B_SZ + boff, sw1);
;     __syncthreads();
;   }
.Lg128_1047:
	s_min_u32 s5, s1, 13
	s_lshl_b32 s82, s5, 7
	s_and_b32 s5, s1, 1
	v_lshl_add_u32 v204, s5, 15, v104
	v_lshl_add_u32 v205, s5, 14, v103
	v_add_u32_e32 v204, v204, v109
	v_add_u32_e32 v205, v205, v109
	s_xor_b32 s5, s5, 1
	s_lshl_b32 s9, s5, 15
	v_lshl_add_u32 v206, s5, 14, v103
	s_lshl_b32 s5, s5, 14
	s_add_i32 s5, s5, 0x10000
	s_waitcnt lgkmcnt(3)
	v_mfma_f32_16x16x32_bf16 v[86:89], v[236:239], v[110:113], v[86:89]
	v_mfma_f32_16x16x32_bf16 v[66:69], v[236:239], v[114:117], v[66:69]
	v_mfma_f32_16x16x32_bf16 v[30:33], v[236:239], v[118:121], v[30:33]
	v_mfma_f32_16x16x32_bf16 v[14:17], v[236:239], v[122:125], v[14:17]
	ds_read_b128 v[236:239], v205
	ds_read_b128 v[220:223], v204
	v_add3_u32 v252, s9, v105, v102
	s_waitcnt vmcnt(5)
	ds_write_b128 v252, v[38:41]
	v_lshl_add_u64 v[38:39], v[90:91], 0, s[82:83]
	global_load_dwordx4 v[38:41], v[38:39], off offset:256
	s_waitcnt lgkmcnt(5)
	v_mfma_f32_16x16x32_bf16 v[82:85], v[240:243], v[110:113], v[82:85]
	v_mfma_f32_16x16x32_bf16 v[62:65], v[240:243], v[114:117], v[62:65]
	v_mfma_f32_16x16x32_bf16 v[26:29], v[240:243], v[118:121], v[26:29]
	v_mfma_f32_16x16x32_bf16 v[10:13], v[240:243], v[122:125], v[10:13]
	ds_read_b128 v[240:243], v205 offset:2048
	ds_read_b128 v[224:227], v204 offset:2048
	v_add3_u32 v252, s9, v106, v102
	s_waitcnt vmcnt(5)
	ds_write_b128 v252, v[42:45]
	v_lshl_add_u64 v[42:43], v[92:93], 0, s[82:83]
	global_load_dwordx4 v[42:45], v[42:43], off offset:256
	v_add3_u32 v252, s9, v107, v102
	s_waitcnt vmcnt(5)
	ds_write_b128 v252, v[46:49]
	v_lshl_add_u64 v[46:47], v[94:95], 0, s[82:83]
	global_load_dwordx4 v[46:49], v[46:47], off offset:256
	s_waitcnt lgkmcnt(8)
	v_mfma_f32_16x16x32_bf16 v[78:81], v[244:247], v[110:113], v[78:81]
	v_mfma_f32_16x16x32_bf16 v[58:61], v[244:247], v[114:117], v[58:61]
	v_mfma_f32_16x16x32_bf16 v[22:25], v[244:247], v[118:121], v[22:25]
	v_mfma_f32_16x16x32_bf16 v[6:9], v[244:247], v[122:125], v[6:9]
	ds_read_b128 v[244:247], v205 offset:4096
	ds_read_b128 v[228:231], v204 offset:4096
	v_add3_u32 v252, s9, v108, v102
	s_waitcnt vmcnt(5)
	ds_write_b128 v252, v[50:53]
	v_lshl_add_u64 v[50:51], v[96:97], 0, s[82:83]
	global_load_dwordx4 v[50:53], v[50:51], off offset:256
	v_add3_u32 v252, s5, v105, v102
	s_waitcnt vmcnt(5)
	ds_write_b128 v252, v[54:57]
	v_lshl_add_u64 v[54:55], v[98:99], 0, s[82:83]
	global_load_dwordx4 v[54:57], v[54:55], off offset:256
	s_waitcnt lgkmcnt(11)
	v_mfma_f32_16x16x32_bf16 v[74:77], v[248:251], v[110:113], v[74:77]
	v_mfma_f32_16x16x32_bf16 v[34:37], v[248:251], v[114:117], v[34:37]
	v_mfma_f32_16x16x32_bf16 v[18:21], v[248:251], v[118:121], v[18:21]
	v_mfma_f32_16x16x32_bf16 v[2:5], v[248:251], v[122:125], v[2:5]
	ds_read_b128 v[248:251], v205 offset:6144
	ds_read_b128 v[232:235], v204 offset:6144
	v_add3_u32 v252, s5, v106, v102
	s_waitcnt vmcnt(5)
	ds_write_b128 v252, v[70:73]
	v_lshl_add_u64 v[70:71], v[100:101], 0, s[82:83]
	global_load_dwordx4 v[70:73], v[70:71], off offset:256
	v_lshlrev_b32_e32 v203, 1, v0
	v_add3_u32 v216, v104, s9, v203
	v_add_u32_e32 v206, v206, v203
	s_waitcnt lgkmcnt(0)
	s_barrier
	ds_read_b128 v[110:113], v216
	ds_read_b128 v[114:117], v216 offset:2048
	ds_read_b128 v[118:121], v216 offset:4096
	ds_read_b128 v[122:125], v216 offset:6144
	v_mfma_f32_16x16x32_bf16 v[86:89], v[236:239], v[220:223], v[86:89]
	v_mfma_f32_16x16x32_bf16 v[66:69], v[236:239], v[224:227], v[66:69]
	v_mfma_f32_16x16x32_bf16 v[30:33], v[236:239], v[228:231], v[30:33]
	v_mfma_f32_16x16x32_bf16 v[14:17], v[236:239], v[232:235], v[14:17]
	ds_read_b128 v[236:239], v206
	v_mfma_f32_16x16x32_bf16 v[82:85], v[240:243], v[220:223], v[82:85]
	v_mfma_f32_16x16x32_bf16 v[62:65], v[240:243], v[224:227], v[62:65]
	v_mfma_f32_16x16x32_bf16 v[26:29], v[240:243], v[228:231], v[26:29]
	v_mfma_f32_16x16x32_bf16 v[10:13], v[240:243], v[232:235], v[10:13]
	ds_read_b128 v[240:243], v206 offset:2048
	v_mfma_f32_16x16x32_bf16 v[78:81], v[244:247], v[220:223], v[78:81]
	v_mfma_f32_16x16x32_bf16 v[58:61], v[244:247], v[224:227], v[58:61]
	v_mfma_f32_16x16x32_bf16 v[22:25], v[244:247], v[228:231], v[22:25]
	v_mfma_f32_16x16x32_bf16 v[6:9], v[244:247], v[232:235], v[6:9]
	ds_read_b128 v[244:247], v206 offset:4096
	v_mfma_f32_16x16x32_bf16 v[74:77], v[248:251], v[220:223], v[74:77]
	v_mfma_f32_16x16x32_bf16 v[34:37], v[248:251], v[224:227], v[34:37]
	v_mfma_f32_16x16x32_bf16 v[18:21], v[248:251], v[228:231], v[18:21]
	v_mfma_f32_16x16x32_bf16 v[2:5], v[248:251], v[232:235], v[2:5]
	ds_read_b128 v[248:251], v206 offset:6144
	s_add_i32 s1, s1, 1
	s_cmp_lg_u32 s1, 16
	s_cbranch_scc1 .Lg128_1047
; DEV int get_tid() { int t = threadIdx.x; asm volatile("" : "+v"(t)); return t; }
; DEV float* hrow(const Params& p, int b, int t) {
;   return (t < 128) ? (float*)(p.ws + OFF_H) + (size_t)(b * 128 + t) * 1024 : p.out + ((size_t)b * 8192 + (t - 128)) * 1024;
; }
; DEV void phase_resid(const Params& p, int b, const bf16_t* A, int K, const bf16_t* Wt, unsigned char* ldsraw) {
;     ...
;     const int tid = get_tid(), lane = tid & 63, wave = tid >> 6, wm = wave >> 1, wn = wave & 1; const int lr = lane & 15, lg = lane >> 4;
; #pragma unroll
;     for (int i = 0; i < 4; i++) {
;       const int t = row0 + wm * 64 + i * 16 + lr;
; #pragma unroll
;       for (int j = 0; j < 4; j++) {
;         float4* d = (float4*)(hrow(p, b, t) + nt * 128 + wn * 64 + j * 16 + lg * 4);
;         float4 v = *d;
;         v.x += acc[i][j][0]; v.y += acc[i][j][1]; v.z += acc[i][j][2]; v.w += acc[i][j][3];
;         *d = v;
;       }
;     }
	s_waitcnt lgkmcnt(0)
	s_waitcnt vmcnt(4)
	v_mov_b32_e32 v42, v181
	s_lshl_b32 s0, s0, 7
	v_ashrrev_i32_e32 v38, 1, v42
	v_and_b32_e32 v38, 0xffffffc0, v38
	v_add_u32_e32 v38, s4, v38
	s_waitcnt vmcnt(3)
	v_and_or_b32 v46, v42, 15, v38
	s_movk_i32 s4, 0x80
	v_add_u32_e32 v40, s3, v46
	v_cmp_gt_i32_e32 vcc, s4, v46
	v_add_u32_e32 v38, 0xffffff80, v46
	v_ashrrev_i32_e32 v39, 31, v40
	v_cndmask_b32_e32 v39, 0, v39, vcc
	v_cndmask_b32_e32 v38, v38, v40, vcc
	v_mov_b32_e32 v47, s8
	v_mov_b32_e32 v48, s39
	v_mov_b32_e32 v49, s7
	s_waitcnt vmcnt(2)
	v_mov_b32_e32 v50, s60
	s_ashr_i32 s1, s0, 31
	v_cndmask_b32_e32 v41, v47, v48, vcc
	v_cndmask_b32_e32 v40, v49, v50, vcc
	v_lshlrev_b64 v[38:39], 12, v[38:39]
	v_and_b32_e32 v0, 64, v42
	v_lshl_add_u64 v[38:39], v[40:41], 0, v[38:39]
	s_lshl_b64 s[0:1], s[0:1], 2
	v_lshl_add_u64 v[38:39], v[38:39], 0, s[0:1]
	v_lshlrev_b32_e32 v0, 2, v0
	v_lshl_add_u64 v[40:41], v[38:39], 0, v[0:1]
	v_and_b32_e32 v38, 48, v42
	v_mov_b32_e32 v39, v1
	v_lshl_add_u64 v[44:45], v[40:41], 0, v[38:39]
	global_load_dwordx4 v[40:43], v[44:45], off
	s_waitcnt vmcnt(0)
	v_pk_add_f32 v[40:41], v[86:87], v[40:41]
	v_pk_add_f32 v[42:43], v[88:89], v[42:43]
	global_store_dwordx4 v[44:45], v[40:43], off
	global_load_dwordx4 v[40:43], v[44:45], off offset:64
	s_waitcnt vmcnt(0)
	v_pk_add_f32 v[40:41], v[82:83], v[40:41]
	v_pk_add_f32 v[42:43], v[84:85], v[42:43]
	global_store_dwordx4 v[44:45], v[40:43], off offset:64
	global_load_dwordx4 v[40:43], v[44:45], off offset:128
	s_waitcnt vmcnt(0)
	v_pk_add_f32 v[40:41], v[78:79], v[40:41]
	v_pk_add_f32 v[42:43], v[80:81], v[42:43]
	global_store_dwordx4 v[44:45], v[40:43], off offset:128
	global_load_dwordx4 v[40:43], v[44:45], off offset:192
	s_waitcnt vmcnt(0)
	v_pk_add_f32 v[40:41], v[74:75], v[40:41]
	v_pk_add_f32 v[42:43], v[76:77], v[42:43]
	global_store_dwordx4 v[44:45], v[40:43], off offset:192
	s_nop 1
	v_or_b32_e32 v40, 16, v46
	v_cmp_gt_i32_e32 vcc, s4, v40
	v_add_u32_e32 v40, s3, v40
	v_add_u32_e32 v42, 0xffffff90, v46
	v_ashrrev_i32_e32 v41, 31, v40
	v_cndmask_b32_e32 v41, 0, v41, vcc
	v_cndmask_b32_e32 v40, v42, v40, vcc
	v_cndmask_b32_e32 v43, v47, v48, vcc
	v_cndmask_b32_e32 v42, v49, v50, vcc
	v_lshlrev_b64 v[40:41], 12, v[40:41]
	v_lshl_add_u64 v[40:41], v[42:43], 0, v[40:41]
	v_lshl_add_u64 v[40:41], v[40:41], 0, s[0:1]
	v_lshl_add_u64 v[40:41], v[40:41], 0, v[0:1]
	v_lshl_add_u64 v[44:45], v[40:41], 0, v[38:39]
	global_load_dwordx4 v[40:43], v[44:45], off
	s_waitcnt vmcnt(0)
	v_pk_add_f32 v[40:41], v[66:67], v[40:41]
	v_pk_add_f32 v[42:43], v[68:69], v[42:43]
	global_store_dwordx4 v[44:45], v[40:43], off
	global_load_dwordx4 v[40:43], v[44:45], off offset:64
	s_waitcnt vmcnt(0)
	v_pk_add_f32 v[40:41], v[62:63], v[40:41]
	v_pk_add_f32 v[42:43], v[64:65], v[42:43]
	global_store_dwordx4 v[44:45], v[40:43], off offset:64
	global_load_dwordx4 v[40:43], v[44:45], off offset:128
	s_waitcnt vmcnt(0)
	v_pk_add_f32 v[40:41], v[58:59], v[40:41]
	v_pk_add_f32 v[42:43], v[60:61], v[42:43]
	global_store_dwordx4 v[44:45], v[40:43], off offset:128
	global_load_dwordx4 v[40:43], v[44:45], off offset:192
	s_waitcnt vmcnt(0)
	v_pk_add_f32 v[34:35], v[34:35], v[40:41]
	v_pk_add_f32 v[36:37], v[36:37], v[42:43]
	global_store_dwordx4 v[44:45], v[34:37], off offset:192
	s_nop 1
	v_or_b32_e32 v34, 32, v46
	v_cmp_gt_i32_e32 vcc, s4, v34
	v_add_u32_e32 v34, s3, v34
	v_add_u32_e32 v36, 0xffffffa0, v46
	v_ashrrev_i32_e32 v35, 31, v34
	v_cndmask_b32_e32 v35, 0, v35, vcc
	v_cndmask_b32_e32 v34, v36, v34, vcc
	v_cndmask_b32_e32 v37, v47, v48, vcc
	v_cndmask_b32_e32 v36, v49, v50, vcc
	v_lshlrev_b64 v[34:35], 12, v[34:35]
	v_lshl_add_u64 v[34:35], v[36:37], 0, v[34:35]
	v_lshl_add_u64 v[34:35], v[34:35], 0, s[0:1]
	v_lshl_add_u64 v[34:35], v[34:35], 0, v[0:1]
	v_lshl_add_u64 v[40:41], v[34:35], 0, v[38:39]
	global_load_dwordx4 v[34:37], v[40:41], off
	s_waitcnt vmcnt(0)
	v_pk_add_f32 v[30:31], v[30:31], v[34:35]
	v_pk_add_f32 v[32:33], v[32:33], v[36:37]
	global_store_dwordx4 v[40:41], v[30:33], off
	global_load_dwordx4 v[30:33], v[40:41], off offset:64
	s_waitcnt vmcnt(0)
	v_pk_add_f32 v[26:27], v[26:27], v[30:31]
	v_pk_add_f32 v[28:29], v[28:29], v[32:33]
	global_store_dwordx4 v[40:41], v[26:29], off offset:64
	global_load_dwordx4 v[26:29], v[40:41], off offset:128
	s_waitcnt vmcnt(0)
	v_pk_add_f32 v[22:23], v[22:23], v[26:27]
	v_pk_add_f32 v[24:25], v[24:25], v[28:29]
	global_store_dwordx4 v[40:41], v[22:25], off offset:128
	global_load_dwordx4 v[22:25], v[40:41], off offset:192
	s_waitcnt vmcnt(0)
	v_pk_add_f32 v[18:19], v[18:19], v[22:23]
	v_pk_add_f32 v[20:21], v[20:21], v[24:25]
	global_store_dwordx4 v[40:41], v[18:21], off offset:192
	s_nop 1
	v_or_b32_e32 v18, 48, v46
	v_cmp_gt_i32_e32 vcc, s4, v18
	v_add_u32_e32 v18, s3, v18
	v_add_u32_e32 v20, 0xffffffb0, v46
	v_ashrrev_i32_e32 v19, 31, v18
	v_cndmask_b32_e32 v19, 0, v19, vcc
	v_cndmask_b32_e32 v18, v20, v18, vcc
	v_cndmask_b32_e32 v21, v47, v48, vcc
	v_cndmask_b32_e32 v20, v49, v50, vcc
	v_lshlrev_b64 v[18:19], 12, v[18:19]
	v_lshl_add_u64 v[18:19], v[20:21], 0, v[18:19]
	v_lshl_add_u64 v[18:19], v[18:19], 0, s[0:1]
	v_lshl_add_u64 v[18:19], v[18:19], 0, v[0:1]
	v_lshl_add_u64 v[22:23], v[18:19], 0, v[38:39]
	global_load_dwordx4 v[18:21], v[22:23], off
	s_waitcnt vmcnt(0)
	v_pk_add_f32 v[14:15], v[14:15], v[18:19]
	v_pk_add_f32 v[16:17], v[16:17], v[20:21]
	global_store_dwordx4 v[22:23], v[14:17], off
	global_load_dwordx4 v[14:17], v[22:23], off offset:64
	s_waitcnt vmcnt(0)
	v_pk_add_f32 v[10:11], v[10:11], v[14:15]
	v_pk_add_f32 v[12:13], v[12:13], v[16:17]
	global_store_dwordx4 v[22:23], v[10:13], off offset:64
	global_load_dwordx4 v[10:13], v[22:23], off offset:128
	s_waitcnt vmcnt(0)
	v_pk_add_f32 v[6:7], v[6:7], v[10:11]
	v_pk_add_f32 v[8:9], v[8:9], v[12:13]
	global_store_dwordx4 v[22:23], v[6:9], off offset:128
	global_load_dwordx4 v[6:9], v[22:23], off offset:192
	s_waitcnt vmcnt(0)
	v_pk_add_f32 v[2:3], v[2:3], v[6:7]
	v_pk_add_f32 v[4:5], v[4:5], v[8:9]
	global_store_dwordx4 v[22:23], v[2:5], off offset:192
	s_branch .LBB0_1044

; template <int BN, bool TRANS = false>
; DEV void gemm256_acc(f32x4 (&acc)[4][BN / 32], const bf16_t* __restrict__ A, int lda, int m_valid,
;                      const bf16_t* __restrict__ Bt, int ldb, int K, bf16_t* lds) {
;     ...
;   const bf16_t* ga0 = A + (size_t)min(crow, m_valid - 1) * lda + ckc;
;   const bf16_t* ga1 = A + (size_t)min(crow + 64, m_valid - 1) * lda + ckc;
;   const bf16_t* ga2 = A + (size_t)min(crow + 128, m_valid - 1) * lda + ckc;
;   const bf16_t* ga3 = A + (size_t)min(crow + 192, m_valid - 1) * lda + ckc;
;   const bf16_t* gb = Bt + (size_t)crow * ldb + ckc;
;   u32x4 ra0, ra1, ra2, ra3, rb0, rb1, rb2, rb3;
;     ...
;   const int nk = K / 64;
;   const int aoff = (wm * 64 + lr) * LS;
;   const int boff = (wn * (BN / 2) + lr) * LS;
;   GLOAD(0)
;   __syncthreads();
;   LSTORE(0)
;   GLOAD(64)
;   __syncthreads();
; DEV void phase_resid(const Params& p, int b, const bf16_t* A, int K, const bf16_t* Wt, unsigned char* ldsraw) {
;     ...
;     int nt, mt; tile_map(item, 32, 4, mt, nt);
;     const int row0 = 128 + mt * 256;
;     f32x4 acc[4][4];
; #pragma unroll
;     for (int i = 0; i < 4; i++)
; #pragma unroll
;       for (int j = 0; j < 4; j++) acc[i][j] = (f32x4){0.f, 0.f, 0.f, 0.f};
;     gemm256_acc<128>(acc, A + (size_t)row0 * K, K, 256, Wt + (size_t)nt * 128 * K, K, K, lds);
.LBB0_1288:
	s_cmpk_lt_i32 s2, 0x100
	s_mov_b64 s[0:1], -1
	s_cbranch_scc0 .LBB0_1292
	s_ashr_i32 s0, s2, 31
	s_lshr_b32 s0, s0, 25
	s_add_i32 s0, s2, s0
	s_ashr_i32 s1, s0, 7
	s_and_b32 s0, s0, 0xffffff80
	s_sub_i32 s0, s2, s0
	s_ashr_i32 s7, s0, 31
	s_lshr_b32 s7, s7, 30
	s_add_i32 s7, s0, s7
	s_ashr_i32 s7, s7, 2
	s_sub_i32 s1, s1, s7
	s_lshl_b32 s1, s1, 2
	s_lshl_b32 s7, s7, 8
	s_add_i32 s0, s1, s0
	s_or_b32 s1, s7, 0x80
	s_mul_i32 s8, s1, 0x1600
	v_readlane_b32 s10, v254, 59
	s_mul_hi_i32 s7, s1, 0x1600
	v_readlane_b32 s11, v254, 60
	s_add_u32 s8, s10, s8
	s_addc_u32 s9, s11, s7
	s_mul_i32 s10, s0, 0xb0000
	v_mov_b32_e32 v28, v181
	s_mul_hi_i32 s7, s0, 0xb0000
	s_add_u32 s10, s12, s10
	s_addc_u32 s11, s13, s7
	v_ashrrev_i32_e32 v29, 3, v28
	v_min_i32_e32 v0, 0xff, v29
	v_mov_b64_e32 v[2:3], s[8:9]
	s_movk_i32 s7, 0x1600
	v_mad_i64_i32 v[4:5], s[8:9], v0, s7, v[2:3]
	v_lshlrev_b32_e32 v0, 4, v28
	v_and_b32_e32 v0, 0x70, v0
	s_waitcnt vmcnt(3)
	v_add_u32_e32 v30, 64, v29
	v_lshl_add_u64 v[90:91], v[4:5], 0, v[0:1]
	v_min_i32_e32 v4, 0xff, v30
	v_mad_i64_i32 v[4:5], s[8:9], v4, s7, v[2:3]
	v_add_u32_e32 v31, 0x80, v29
	v_lshl_add_u64 v[92:93], v[4:5], 0, v[0:1]
	v_min_i32_e32 v4, 0xff, v31
	v_mad_i64_i32 v[4:5], s[8:9], v4, s7, v[2:3]
	v_add_u32_e32 v32, 0xc0, v29
	v_lshl_add_u64 v[94:95], v[4:5], 0, v[0:1]
	v_min_i32_e32 v4, 0xff, v32
	v_mad_i64_i32 v[2:3], s[8:9], v4, s7, v[2:3]
	v_lshl_add_u64 v[96:97], v[2:3], 0, v[0:1]
	v_mov_b64_e32 v[2:3], s[10:11]
	v_mad_i64_i32 v[2:3], s[8:9], v29, s7, v[2:3]
	v_lshl_add_u64 v[98:99], v[2:3], 0, v[0:1]
	global_load_dwordx4 v[2:5], v[90:91], off
	global_load_dwordx4 v[6:9], v[92:93], off
	global_load_dwordx4 v[10:13], v[94:95], off
	global_load_dwordx4 v[14:17], v[96:97], off
	global_load_dwordx4 v[18:21], v[98:99], off
	v_lshrrev_b32_e32 v0, 4, v28
	v_xor_b32_e32 v35, v0, v28
	s_mov_b32 s7, 0x58000
	v_lshlrev_b32_e32 v35, 3, v35
	v_add_co_u32_e32 v26, vcc, s7, v98
	v_bfe_u32 v34, v28, 1, 3
	v_and_b32_e32 v35, 56, v35
	v_addc_co_u32_e32 v27, vcc, 0, v99, vcc
	v_bitop3_b32 v0, v0, v34, 3 bitop3:0x6c
	v_lshlrev_b32_e32 v34, 6, v29
	v_lshlrev_b32_e32 v29, 7, v29
	v_lshlrev_b32_e32 v102, 1, v35
	global_load_dwordx4 v[22:25], v[26:27], off
	v_lshlrev_b32_e32 v36, 6, v30
	v_lshlrev_b32_e32 v30, 7, v30
	v_lshlrev_b32_e32 v37, 6, v31
	v_lshlrev_b32_e32 v31, 7, v31
	v_lshlrev_b32_e32 v58, 6, v32
	v_lshlrev_b32_e32 v32, 7, v32
	v_add3_u32 v35, 0, v29, v102
	s_barrier
	global_load_dwordx4 v[38:41], v[90:91], off offset:128
	global_load_dwordx4 v[42:45], v[92:93], off offset:128
	global_load_dwordx4 v[46:49], v[94:95], off offset:128
	global_load_dwordx4 v[50:53], v[96:97], off offset:128
	v_add3_u32 v54, 0, v30, v102
	v_add3_u32 v31, 0, v31, v102
	v_add3_u32 v32, 0, v32, v102
	v_add3_u32 v29, s66, v29, v102
	v_lshrrev_b32_e32 v33, 1, v28
	v_lshlrev_b32_e32 v0, 3, v0
	v_xor_b32_e32 v59, 32, v0
	v_add3_u32 v30, s66, v30, v102
	s_mov_b64 s[8:9], 0x58000
	s_mov_b32 s7, 0
	v_lshl_add_u64 v[100:101], v[98:99], 0, s[8:9]
	v_lshlrev_b32_e32 v105, 1, v34
	v_lshlrev_b32_e32 v106, 1, v36
	v_lshlrev_b32_e32 v107, 1, v37
	v_lshlrev_b32_e32 v108, 1, v58
	v_lshlrev_b32_e32 v109, 1, v59
	s_waitcnt vmcnt(9)
	ds_write_b128 v35, v[2:5]
	s_waitcnt vmcnt(8)
	ds_write_b128 v54, v[6:9]
	s_waitcnt vmcnt(7)
	ds_write_b128 v31, v[10:13]
	s_waitcnt vmcnt(6)
	ds_write_b128 v32, v[14:17]
	s_waitcnt vmcnt(5)
	ds_write_b128 v29, v[18:21]
	global_load_dwordx4 v[54:57], v[98:99], off offset:128
	global_load_dwordx4 v[70:73], v[26:27], off offset:128
	v_lshlrev_b32_e32 v2, 7, v28
	v_and_b32_e32 v2, 0x2780, v2
	v_add_u32_e32 v103, s66, v2
	v_and_b32_e32 v2, 15, v28
	v_and_or_b32 v2, v33, s62, v2
	v_lshl_add_u32 v104, v2, 7, 0
	v_mov_b32_e32 v2, 0
	v_mov_b32_e32 v3, v2
	v_mov_b32_e32 v4, v2
	v_mov_b32_e32 v5, v2
	v_mov_b32_e32 v6, v2
	v_mov_b32_e32 v7, v2
	v_mov_b32_e32 v8, v2
	s_waitcnt vmcnt(6)
	ds_write_b128 v30, v[22:25]
	v_mov_b32_e32 v9, v2
	v_mov_b32_e32 v10, v2
	v_mov_b32_e32 v11, v2
	v_mov_b32_e32 v12, v2
	v_mov_b32_e32 v13, v2
	v_mov_b32_e32 v14, v2
	v_mov_b32_e32 v15, v2
	v_mov_b32_e32 v16, v2
	v_mov_b32_e32 v17, v2
	v_mov_b32_e32 v18, v2
	v_mov_b32_e32 v19, v2
	v_mov_b32_e32 v20, v2
	v_mov_b32_e32 v21, v2
	v_mov_b32_e32 v22, v2
	v_mov_b32_e32 v23, v2
	v_mov_b32_e32 v24, v2
	v_mov_b32_e32 v25, v2
	v_mov_b32_e32 v26, v2
	v_mov_b32_e32 v27, v2
	v_mov_b32_e32 v28, v2
	v_mov_b32_e32 v29, v2
	v_mov_b32_e32 v30, v2
	v_mov_b32_e32 v31, v2
	v_mov_b32_e32 v32, v2
	v_mov_b32_e32 v33, v2
	v_mov_b32_e32 v34, v2
	v_mov_b32_e32 v35, v2
	v_mov_b32_e32 v36, v2
	v_mov_b32_e32 v37, v2
	v_mov_b32_e32 v58, v2
	v_mov_b32_e32 v59, v2
	v_mov_b32_e32 v60, v2
	v_mov_b32_e32 v61, v2
	v_mov_b32_e32 v62, v2
	v_mov_b32_e32 v63, v2
	v_mov_b32_e32 v64, v2
	v_mov_b32_e32 v65, v2
	v_mov_b32_e32 v66, v2
	v_mov_b32_e32 v67, v2
	v_mov_b32_e32 v68, v2
	v_mov_b32_e32 v69, v2
	v_mov_b32_e32 v74, v2
	v_mov_b32_e32 v75, v2
	v_mov_b32_e32 v76, v2
	v_mov_b32_e32 v77, v2
	v_mov_b32_e32 v78, v2
	v_mov_b32_e32 v79, v2
	v_mov_b32_e32 v80, v2
	v_mov_b32_e32 v81, v2
	v_mov_b32_e32 v82, v2
	v_mov_b32_e32 v83, v2
	v_mov_b32_e32 v84, v2
	v_mov_b32_e32 v85, v2
	v_mov_b32_e32 v86, v2
	v_mov_b32_e32 v87, v2
	v_mov_b32_e32 v88, v2
	v_mov_b32_e32 v89, v2
	s_waitcnt lgkmcnt(0)
	s_barrier
	v_lshlrev_b32_e32 v203, 1, v0
	v_add_u32_e32 v216, v104, v203
	v_add_u32_e32 v206, v103, v203
	ds_read_b128 v[110:113], v216
	ds_read_b128 v[114:117], v216 offset:2048
	ds_read_b128 v[118:121], v216 offset:4096
	ds_read_b128 v[122:125], v216 offset:6144
	ds_read_b128 v[236:239], v206
	ds_read_b128 v[240:243], v206 offset:2048
	ds_read_b128 v[244:247], v206 offset:4096
	ds_read_b128 v[248:251], v206 offset:6144
; #define MFMA(a, b, c) __builtin_amdgcn_mfma_f32_16x16x32_bf16(a, b, c, 0, 0, 0)
; template <int BN, bool TRANS>
; DEV void gemm256_kstep(f32x4 (&acc)[4][BN / 32], const bf16_t* as, const bf16_t* bs, int sw) {
;   constexpr int LS = 64, NJ = BN / 32;
;   bf16x8 a[4];
; #pragma unroll
;   for (int i = 0; i < 4; i++) a[i] = *(const bf16x8*)(as + i * 16 * LS + sw);
; #pragma unroll
;   for (int j = 0; j < NJ; j++) {
;     bf16x8 bb = *(const bf16x8*)(bs + j * 16 * LS + sw);
; #pragma unroll
;     for (int i = 0; i < 4; i++) acc[i][j] = TRANS ? MFMA(a[i], bb, acc[i][j]) : MFMA(bb, a[i], acc[i][j]);
;   }
; }
; template <int BN, bool TRANS = false>
; DEV void gemm256_acc(f32x4 (&acc)[4][BN / 32], const bf16_t* __restrict__ A, int lda, int m_valid,
;                      const bf16_t* __restrict__ Bt, int ldb, int K, bf16_t* lds) {
;     ...
;   for (int kt = 0; kt < nk; kt++) {
;     const int cur = kt & 1;
;     gemm256_kstep<BN, TRANS>(acc, As + cur * A_SZ + aoff, Bs + cur * B_SZ + boff, sw0);
;     __builtin_amdgcn_sched_barrier(0);
;     LSTORE(cur ^ 1)
;     {
;       const int kn = (kt + 2 < nk) ? kt + 2 : nk - 1;
;       GLOAD(kn * 64)
;     }
;     __builtin_amdgcn_sched_barrier(0);
;     gemm256_kstep<BN, TRANS>(acc, As + cur * A_SZ + aoff, Bs + cur * B_SZ + boff, sw1);
;     __syncthreads();
;   }
.Lg128_1290:
	s_min_u32 s8, s7, 41
	s_lshl_b32 s82, s8, 7
	s_and_b32 s8, s7, 1
	v_lshl_add_u32 v204, s8, 15, v104
	v_lshl_add_u32 v205, s8, 14, v103
	v_add_u32_e32 v204, v204, v109
	v_add_u32_e32 v205, v205, v109
	s_xor_b32 s8, s8, 1
	s_lshl_b32 s9, s8, 15
	v_lshl_add_u32 v206, s8, 14, v103
	s_lshl_b32 s8, s8, 14
	s_add_i32 s8, s8, 0x10000
	s_waitcnt lgkmcnt(3)
	v_mfma_f32_16x16x32_bf16 v[86:89], v[236:239], v[110:113], v[86:89]
	v_mfma_f32_16x16x32_bf16 v[66:69], v[236:239], v[114:117], v[66:69]
	v_mfma_f32_16x16x32_bf16 v[30:33], v[236:239], v[118:121], v[30:33]
	v_mfma_f32_16x16x32_bf16 v[14:17], v[236:239], v[122:125], v[14:17]
	ds_read_b128 v[236:239], v205
	ds_read_b128 v[220:223], v204
	v_add3_u32 v252, s9, v105, v102
	s_waitcnt vmcnt(5)
	ds_write_b128 v252, v[38:41]
	v_lshl_add_u64 v[38:39], v[90:91], 0, s[82:83]
	global_load_dwordx4 v[38:41], v[38:39], off offset:256
	s_waitcnt lgkmcnt(5)
	v_mfma_f32_16x16x32_bf16 v[82:85], v[240:243], v[110:113], v[82:85]
	v_mfma_f32_16x16x32_bf16 v[62:65], v[240:243], v[114:117], v[62:65]
	v_mfma_f32_16x16x32_bf16 v[26:29], v[240:243], v[118:121], v[26:29]
	v_mfma_f32_16x16x32_bf16 v[10:13], v[240:243], v[122:125], v[10:13]
	ds_read_b128 v[240:243], v205 offset:2048
	ds_read_b128 v[224:227], v204 offset:2048
	v_add3_u32 v252, s9, v106, v102
	s_waitcnt vmcnt(5)
	ds_write_b128 v252, v[42:45]
	v_lshl_add_u64 v[42:43], v[92:93], 0, s[82:83]
	global_load_dwordx4 v[42:45], v[42:43], off offset:256
	v_add3_u32 v252, s9, v107, v102
	s_waitcnt vmcnt(5)
	ds_write_b128 v252, v[46:49]
	v_lshl_add_u64 v[46:47], v[94:95], 0, s[82:83]
	global_load_dwordx4 v[46:49], v[46:47], off offset:256
	s_waitcnt lgkmcnt(8)
	v_mfma_f32_16x16x32_bf16 v[78:81], v[244:247], v[110:113], v[78:81]
	v_mfma_f32_16x16x32_bf16 v[58:61], v[244:247], v[114:117], v[58:61]
	v_mfma_f32_16x16x32_bf16 v[22:25], v[244:247], v[118:121], v[22:25]
	v_mfma_f32_16x16x32_bf16 v[6:9], v[244:247], v[122:125], v[6:9]
	ds_read_b128 v[244:247], v205 offset:4096
	ds_read_b128 v[228:231], v204 offset:4096
	v_add3_u32 v252, s9, v108, v102
	s_waitcnt vmcnt(5)
	ds_write_b128 v252, v[50:53]
	v_lshl_add_u64 v[50:51], v[96:97], 0, s[82:83]
	global_load_dwordx4 v[50:53], v[50:51], off offset:256
	v_add3_u32 v252, s8, v105, v102
	s_waitcnt vmcnt(5)
	ds_write_b128 v252, v[54:57]
	v_lshl_add_u64 v[54:55], v[98:99], 0, s[82:83]
	global_load_dwordx4 v[54:57], v[54:55], off offset:256
	s_waitcnt lgkmcnt(11)
	v_mfma_f32_16x16x32_bf16 v[74:77], v[248:251], v[110:113], v[74:77]
	v_mfma_f32_16x16x32_bf16 v[34:37], v[248:251], v[114:117], v[34:37]
	v_mfma_f32_16x16x32_bf16 v[18:21], v[248:251], v[118:121], v[18:21]
	v_mfma_f32_16x16x32_bf16 v[2:5], v[248:251], v[122:125], v[2:5]
	ds_read_b128 v[248:251], v205 offset:6144
	ds_read_b128 v[232:235], v204 offset:6144
	v_add3_u32 v252, s8, v106, v102
	s_waitcnt vmcnt(5)
	ds_write_b128 v252, v[70:73]
	v_lshl_add_u64 v[70:71], v[100:101], 0, s[82:83]
	global_load_dwordx4 v[70:73], v[70:71], off offset:256
	v_lshlrev_b32_e32 v203, 1, v0
	v_add3_u32 v216, v104, s9, v203
	v_add_u32_e32 v206, v206, v203
	s_waitcnt lgkmcnt(0)
	s_barrier
	ds_read_b128 v[110:113], v216
	ds_read_b128 v[114:117], v216 offset:2048
	ds_read_b128 v[118:121], v216 offset:4096
	ds_read_b128 v[122:125], v216 offset:6144
	v_mfma_f32_16x16x32_bf16 v[86:89], v[236:239], v[220:223], v[86:89]
	v_mfma_f32_16x16x32_bf16 v[66:69], v[236:239], v[224:227], v[66:69]
	v_mfma_f32_16x16x32_bf16 v[30:33], v[236:239], v[228:231], v[30:33]
	v_mfma_f32_16x16x32_bf16 v[14:17], v[236:239], v[232:235], v[14:17]
	ds_read_b128 v[236:239], v206
	v_mfma_f32_16x16x32_bf16 v[82:85], v[240:243], v[220:223], v[82:85]
	v_mfma_f32_16x16x32_bf16 v[62:65], v[240:243], v[224:227], v[62:65]
	v_mfma_f32_16x16x32_bf16 v[26:29], v[240:243], v[228:231], v[26:29]
	v_mfma_f32_16x16x32_bf16 v[10:13], v[240:243], v[232:235], v[10:13]
	ds_read_b128 v[240:243], v206 offset:2048
	v_mfma_f32_16x16x32_bf16 v[78:81], v[244:247], v[220:223], v[78:81]
	v_mfma_f32_16x16x32_bf16 v[58:61], v[244:247], v[224:227], v[58:61]
	v_mfma_f32_16x16x32_bf16 v[22:25], v[244:247], v[228:231], v[22:25]
	v_mfma_f32_16x16x32_bf16 v[6:9], v[244:247], v[232:235], v[6:9]
	ds_read_b128 v[244:247], v206 offset:4096
	v_mfma_f32_16x16x32_bf16 v[74:77], v[248:251], v[220:223], v[74:77]
	v_mfma_f32_16x16x32_bf16 v[34:37], v[248:251], v[224:227], v[34:37]
	v_mfma_f32_16x16x32_bf16 v[18:21], v[248:251], v[228:231], v[18:21]
	v_mfma_f32_16x16x32_bf16 v[2:5], v[248:251], v[232:235], v[2:5]
	ds_read_b128 v[248:251], v206 offset:6144
	s_add_i32 s7, s7, 1
	s_cmp_lg_u32 s7, 44
	s_cbranch_scc1 .Lg128_1290
; DEV int get_tid() { int t = threadIdx.x; asm volatile("" : "+v"(t)); return t; }
; DEV float* hrow(const Params& p, int b, int t) {
;   return (t < 128) ? (float*)(p.ws + OFF_H) + (size_t)(b * 128 + t) * 1024 : p.out + ((size_t)b * 8192 + (t - 128)) * 1024;
; }
; DEV void phase_resid(const Params& p, int b, const bf16_t* A, int K, const bf16_t* Wt, unsigned char* ldsraw) {
;     ...
;     const int tid = get_tid(), lane = tid & 63, wave = tid >> 6, wm = wave >> 1, wn = wave & 1; const int lr = lane & 15, lg = lane >> 4;
; #pragma unroll
;     for (int i = 0; i < 4; i++) {
;       const int t = row0 + wm * 64 + i * 16 + lr;
; #pragma unroll
;       for (int j = 0; j < 4; j++) {
;         float4* d = (float4*)(hrow(p, b, t) + nt * 128 + wn * 64 + j * 16 + lg * 4);
;         float4 v = *d;
;         v.x += acc[i][j][0]; v.y += acc[i][j][1]; v.z += acc[i][j][2]; v.w += acc[i][j][3];
;         *d = v;
;       }
;     }
	s_waitcnt lgkmcnt(0)
	s_waitcnt vmcnt(4)
	v_mov_b32_e32 v42, v181
	s_lshl_b32 s0, s0, 7
	v_ashrrev_i32_e32 v38, 1, v42
	v_and_b32_e32 v38, 0xffffffc0, v38
	v_add_u32_e32 v38, s1, v38
	s_waitcnt vmcnt(3)
	v_and_or_b32 v46, v42, 15, v38
	v_add_u32_e32 v40, s3, v46
	v_cmp_gt_i32_e32 vcc, s52, v46
	v_add_u32_e32 v38, 0xffffff80, v46
	v_ashrrev_i32_e32 v39, 31, v40
	v_cndmask_b32_e32 v39, 0, v39, vcc
	v_cndmask_b32_e32 v38, v38, v40, vcc
	v_mov_b32_e32 v47, s6
	v_mov_b32_e32 v48, s39
	v_mov_b32_e32 v49, s5
	s_waitcnt vmcnt(2)
	v_mov_b32_e32 v50, s60
	s_ashr_i32 s1, s0, 31
	v_cndmask_b32_e32 v41, v47, v48, vcc
	v_cndmask_b32_e32 v40, v49, v50, vcc
	v_lshlrev_b64 v[38:39], 12, v[38:39]
	v_and_b32_e32 v0, 64, v42
	v_lshl_add_u64 v[38:39], v[40:41], 0, v[38:39]
	s_lshl_b64 s[0:1], s[0:1], 2
	v_lshl_add_u64 v[38:39], v[38:39], 0, s[0:1]
	v_lshlrev_b32_e32 v0, 2, v0
	v_lshl_add_u64 v[40:41], v[38:39], 0, v[0:1]
	v_and_b32_e32 v38, 48, v42
	v_mov_b32_e32 v39, v1
	v_lshl_add_u64 v[44:45], v[40:41], 0, v[38:39]
	global_load_dwordx4 v[40:43], v[44:45], off
	s_waitcnt vmcnt(0)
	v_pk_add_f32 v[40:41], v[86:87], v[40:41]
	v_pk_add_f32 v[42:43], v[88:89], v[42:43]
	global_store_dwordx4 v[44:45], v[40:43], off
	global_load_dwordx4 v[40:43], v[44:45], off offset:64
	s_waitcnt vmcnt(0)
	v_pk_add_f32 v[40:41], v[82:83], v[40:41]
	v_pk_add_f32 v[42:43], v[84:85], v[42:43]
	global_store_dwordx4 v[44:45], v[40:43], off offset:64
	global_load_dwordx4 v[40:43], v[44:45], off offset:128
	s_waitcnt vmcnt(0)
	v_pk_add_f32 v[40:41], v[78:79], v[40:41]
	v_pk_add_f32 v[42:43], v[80:81], v[42:43]
	global_store_dwordx4 v[44:45], v[40:43], off offset:128
	global_load_dwordx4 v[40:43], v[44:45], off offset:192
	s_waitcnt vmcnt(0)
	v_pk_add_f32 v[40:41], v[74:75], v[40:41]
	v_pk_add_f32 v[42:43], v[76:77], v[42:43]
	global_store_dwordx4 v[44:45], v[40:43], off offset:192
	s_nop 1
	v_or_b32_e32 v40, 16, v46
	v_cmp_gt_i32_e32 vcc, s52, v40
	v_add_u32_e32 v40, s3, v40
	v_add_u32_e32 v42, 0xffffff90, v46
	v_ashrrev_i32_e32 v41, 31, v40
	v_cndmask_b32_e32 v41, 0, v41, vcc
	v_cndmask_b32_e32 v40, v42, v40, vcc
	v_cndmask_b32_e32 v43, v47, v48, vcc
	v_cndmask_b32_e32 v42, v49, v50, vcc
	v_lshlrev_b64 v[40:41], 12, v[40:41]
	v_lshl_add_u64 v[40:41], v[42:43], 0, v[40:41]
	v_lshl_add_u64 v[40:41], v[40:41], 0, s[0:1]
	v_lshl_add_u64 v[40:41], v[40:41], 0, v[0:1]
	v_lshl_add_u64 v[44:45], v[40:41], 0, v[38:39]
	global_load_dwordx4 v[40:43], v[44:45], off
	s_waitcnt vmcnt(0)
	v_pk_add_f32 v[40:41], v[66:67], v[40:41]
	v_pk_add_f32 v[42:43], v[68:69], v[42:43]
	global_store_dwordx4 v[44:45], v[40:43], off
	global_load_dwordx4 v[40:43], v[44:45], off offset:64
	s_waitcnt vmcnt(0)
	v_pk_add_f32 v[40:41], v[62:63], v[40:41]
	v_pk_add_f32 v[42:43], v[64:65], v[42:43]
	global_store_dwordx4 v[44:45], v[40:43], off offset:64
	global_load_dwordx4 v[40:43], v[44:45], off offset:128
	s_waitcnt vmcnt(0)
	v_pk_add_f32 v[40:41], v[58:59], v[40:41]
	v_pk_add_f32 v[42:43], v[60:61], v[42:43]
	global_store_dwordx4 v[44:45], v[40:43], off offset:128
	global_load_dwordx4 v[40:43], v[44:45], off offset:192
	s_waitcnt vmcnt(0)
	v_pk_add_f32 v[34:35], v[34:35], v[40:41]
	v_pk_add_f32 v[36:37], v[36:37], v[42:43]
	global_store_dwordx4 v[44:45], v[34:37], off offset:192
	s_nop 1
	v_or_b32_e32 v34, 32, v46
	v_cmp_gt_i32_e32 vcc, s52, v34
	v_add_u32_e32 v34, s3, v34
	v_add_u32_e32 v36, 0xffffffa0, v46
	v_ashrrev_i32_e32 v35, 31, v34
	v_cndmask_b32_e32 v35, 0, v35, vcc
	v_cndmask_b32_e32 v34, v36, v34, vcc
	v_cndmask_b32_e32 v37, v47, v48, vcc
	v_cndmask_b32_e32 v36, v49, v50, vcc
	v_lshlrev_b64 v[34:35], 12, v[34:35]
	v_lshl_add_u64 v[34:35], v[36:37], 0, v[34:35]
	v_lshl_add_u64 v[34:35], v[34:35], 0, s[0:1]
	v_lshl_add_u64 v[34:35], v[34:35], 0, v[0:1]
	v_lshl_add_u64 v[40:41], v[34:35], 0, v[38:39]
	global_load_dwordx4 v[34:37], v[40:41], off
	s_waitcnt vmcnt(0)
	v_pk_add_f32 v[30:31], v[30:31], v[34:35]
	v_pk_add_f32 v[32:33], v[32:33], v[36:37]
	global_store_dwordx4 v[40:41], v[30:33], off
	global_load_dwordx4 v[30:33], v[40:41], off offset:64
	s_waitcnt vmcnt(0)
	v_pk_add_f32 v[26:27], v[26:27], v[30:31]
	v_pk_add_f32 v[28:29], v[28:29], v[32:33]
	global_store_dwordx4 v[40:41], v[26:29], off offset:64
	global_load_dwordx4 v[26:29], v[40:41], off offset:128
	s_waitcnt vmcnt(0)
	v_pk_add_f32 v[22:23], v[22:23], v[26:27]
	v_pk_add_f32 v[24:25], v[24:25], v[28:29]
	global_store_dwordx4 v[40:41], v[22:25], off offset:128
	global_load_dwordx4 v[22:25], v[40:41], off offset:192
	s_waitcnt vmcnt(0)
	v_pk_add_f32 v[18:19], v[18:19], v[22:23]
	v_pk_add_f32 v[20:21], v[20:21], v[24:25]
	global_store_dwordx4 v[40:41], v[18:21], off offset:192
	s_nop 1
	v_or_b32_e32 v18, 48, v46
	v_cmp_gt_i32_e32 vcc, s52, v18
	v_add_u32_e32 v18, s3, v18
	v_add_u32_e32 v20, 0xffffffb0, v46
	v_ashrrev_i32_e32 v19, 31, v18
	v_cndmask_b32_e32 v19, 0, v19, vcc
	v_cndmask_b32_e32 v18, v20, v18, vcc
	v_cndmask_b32_e32 v21, v47, v48, vcc
	v_cndmask_b32_e32 v20, v49, v50, vcc
	v_lshlrev_b64 v[18:19], 12, v[18:19]
	v_lshl_add_u64 v[18:19], v[20:21], 0, v[18:19]
	v_lshl_add_u64 v[18:19], v[18:19], 0, s[0:1]
	v_lshl_add_u64 v[18:19], v[18:19], 0, v[0:1]
	v_lshl_add_u64 v[22:23], v[18:19], 0, v[38:39]
	global_load_dwordx4 v[18:21], v[22:23], off
	s_waitcnt vmcnt(0)
	v_pk_add_f32 v[14:15], v[14:15], v[18:19]
	v_pk_add_f32 v[16:17], v[16:17], v[20:21]
	global_store_dwordx4 v[22:23], v[14:17], off
	global_load_dwordx4 v[14:17], v[22:23], off offset:64
	s_waitcnt vmcnt(0)
	v_pk_add_f32 v[10:11], v[10:11], v[14:15]
	v_pk_add_f32 v[12:13], v[12:13], v[16:17]
	global_store_dwordx4 v[22:23], v[10:13], off offset:64
	global_load_dwordx4 v[10:13], v[22:23], off offset:128
	s_waitcnt vmcnt(0)
	v_pk_add_f32 v[6:7], v[6:7], v[10:11]
	v_pk_add_f32 v[8:9], v[8:9], v[12:13]
	global_store_dwordx4 v[22:23], v[6:9], off offset:128
	global_load_dwordx4 v[6:9], v[22:23], off offset:192
	s_waitcnt vmcnt(0)
	v_pk_add_f32 v[2:3], v[2:3], v[6:7]
	v_pk_add_f32 v[4:5], v[4:5], v[8:9]
	global_store_dwordx4 v[22:23], v[2:5], off offset:192
	s_branch .LBB0_1287
